# speedup vs baseline: 1.0115x; 1.0055x over previous
; DI int my_tid() { int t = threadIdx.x; asm volatile("" : "+v"(t)); return t; }
; DI int my_block() { int b = blockIdx.x; asm volatile("" : "+s"(b)); return b; }
; DI int my_grid() { int g = gridDim.x; asm volatile("" : "+s"(g)); return g; }
; DI unsigned pk2(float lo, float hi) { unsigned r; asm("v_cvt_pk_bf16_f32 %0, %1, %2" : "=v"(r) : "v"(lo), "v"(hi)); return r; }
; DI void rms_row(const float* xrow, const float* g, u16* orow, int lane) {
;   const f32x4* xr = (const f32x4*)xrow + lane; const f32x4* gr = (const f32x4*)g + lane;
;   f32x4 v[8]; float s = 0.f;
; #pragma unroll
;   for (int j = 0; j < 8; ++j) { v[j] = xr[64 * j]; s += (v[j].x * v[j].x + v[j].y * v[j].y) + (v[j].z * v[j].z + v[j].w * v[j].w); }
;   const float rstd = rsqrtf(wave_sum(s, lane) * (1.f / DM) + EPS);
;   u32x2* o8 = (u32x2*)orow + lane;
; #pragma unroll
;   for (int j = 0; j < 8; ++j) { const f32x4 gg = gr[64 * j]; u32x2 o; o.x = pk2(v[j].x * rstd * gg.x, v[j].y * rstd * gg.y); o.y = pk2(v[j].z * rstd * gg.z, v[j].w * rstd * gg.w); o8[64 * j] = o; }
; }
; DI void phase_rms_next(CP& p) {
;   const int tid = my_tid(), wave = tid >> 6, lane = tid & 63;
;   u16* h = (u16*)(p.ws + WS_H);
;   for (int r = my_block() * 8 + wave; r < TVAL; r += my_grid() * 8) rms_row(p.out + (size_t)r * DM, p.in[8] + DM, h + (size_t)r * DM, lane);
; }
.LBB0_19:
	v_ashrrev_i32_e32 v5, 31, v4
	v_lshlrev_b64 v[0:1], 13, v[4:5]
	v_lshl_add_u64 v[0:1], v[6:7], 0, v[0:1]
	global_load_dwordx4 v[22:25], v[0:1], off
	global_load_dwordx4 v[26:29], v[0:1], off offset:1024
	global_load_dwordx4 v[30:33], v[0:1], off offset:2048
	global_load_dwordx4 v[34:37], v[0:1], off offset:3072
	v_add_co_u32_e32 v46, vcc, s78, v0
	s_mov_b32 s0, s28
	s_nop 0
	v_addc_co_u32_e32 v47, vcc, 0, v1, vcc
	global_load_dwordx4 v[38:41], v[46:47], off
	global_load_dwordx4 v[42:45], v[46:47], off offset:1024
	global_load_dwordx4 v[0:3], v[46:47], off offset:3072
	s_nop 0
	global_load_dwordx4 v[46:49], v[46:47], off offset:2048
	s_nop 0
	global_load_dwordx4 v[50:53], v[8:9], off
	global_load_dwordx4 v[100:103], v[8:9], off offset:1024
	global_load_dwordx4 v[104:107], v[8:9], off offset:2048
	global_load_dwordx4 v[108:111], v[8:9], off offset:3072
	global_load_dwordx4 v[112:115], v[12:13], off
	global_load_dwordx4 v[116:119], v[14:15], off
	global_load_dwordx4 v[120:123], v[16:17], off
	global_load_dwordx4 v[124:127], v[18:19], off
	s_waitcnt vmcnt(15)
	v_mov_b32_e32 v56, v23
	s_waitcnt vmcnt(14)
	v_mov_b32_e32 v57, v27
	v_mov_b32_e32 v60, v25
	v_mov_b32_e32 v61, v29
	v_mov_b32_e32 v54, v22
	v_mov_b32_e32 v55, v26
	v_mov_b32_e32 v58, v24
	v_mov_b32_e32 v59, v28
	s_waitcnt vmcnt(13)
	v_pk_mul_f32 v[62:63], v[32:33], v[32:33]
	v_pk_mul_f32 v[64:65], v[30:31], v[30:31]
	v_pk_mul_f32 v[56:57], v[56:57], v[56:57]
	v_pk_mul_f32 v[60:61], v[60:61], v[60:61]
	v_pk_mov_b32 v[70:71], v[64:65], v[62:63] op_sel:[1,0]
	v_mov_b32_e32 v65, v63
	v_pk_fma_f32 v[54:55], v[54:55], v[54:55], v[56:57]
	v_pk_fma_f32 v[56:57], v[58:59], v[58:59], v[60:61]
	s_waitcnt vmcnt(12)
	v_mul_f32_e32 v66, v35, v35
	v_mul_f32_e32 v68, v37, v37
	v_pk_add_f32 v[58:59], v[70:71], v[64:65]
	v_pk_add_f32 v[54:55], v[54:55], v[56:57]
	s_waitcnt vmcnt(11)
	v_mul_f32_e32 v21, v38, v38
	v_mul_f32_e32 v75, v39, v39
	v_mul_f32_e32 v77, v40, v40
	v_mul_f32_e32 v78, v41, v41
	v_pk_fma_f32 v[62:63], v[34:35], v[34:35], v[66:67] op_sel_hi:[1,1,0]
	v_pk_fma_f32 v[66:67], v[36:37], v[36:37], v[68:69] op_sel_hi:[1,1,0]
	v_pk_add_f32 v[56:57], v[58:59], v[58:59] op_sel:[0,1] op_sel_hi:[1,0]
	v_pk_add_f32 v[54:55], v[54:55], v[54:55] op_sel:[0,1] op_sel_hi:[1,0]
	s_waitcnt vmcnt(10)
	v_pk_mul_f32 v[68:69], v[44:45], v[44:45]
	v_pk_mul_f32 v[72:73], v[42:43], v[42:43]
	v_mov_b32_e32 v63, v77
	v_mov_b32_e32 v67, v78
	v_mov_b32_e32 v57, v75
	v_mov_b32_e32 v55, v21
	v_pk_mov_b32 v[60:61], v[72:73], v[68:69] op_sel:[1,0]
	v_mov_b32_e32 v73, v69
	v_pk_add_f32 v[58:59], v[62:63], v[66:67]
	v_pk_add_f32 v[54:55], v[54:55], v[56:57]
	s_waitcnt vmcnt(8)
	v_mul_f32_e32 v74, v47, v47
	v_mul_f32_e32 v76, v49, v49
	v_pk_add_f32 v[60:61], v[60:61], v[72:73]
	v_pk_add_f32 v[54:55], v[54:55], v[58:59]
	v_mul_f32_e32 v79, v0, v0
	v_mul_f32_e32 v80, v1, v1
	v_mul_f32_e32 v81, v2, v2
	v_mul_f32_e32 v82, v3, v3
	v_pk_fma_f32 v[64:65], v[46:47], v[46:47], v[74:75] op_sel_hi:[1,1,0]
	v_pk_fma_f32 v[68:69], v[48:49], v[48:49], v[76:77] op_sel_hi:[1,1,0]
	v_pk_add_f32 v[60:61], v[60:61], v[60:61] op_sel:[0,1] op_sel_hi:[1,0]
	v_pk_add_f32 v[54:55], v[54:55], v[54:55] op_sel:[0,1] op_sel_hi:[1,0]
	v_mov_b32_e32 v65, v81
	v_mov_b32_e32 v69, v82
	v_mov_b32_e32 v61, v80
	v_mov_b32_e32 v55, v79
	v_pk_add_f32 v[62:63], v[64:65], v[68:69]
	v_pk_add_f32 v[54:55], v[54:55], v[60:61]
	s_nop 0
	v_pk_add_f32 v[54:55], v[54:55], v[62:63]
	s_nop 0
	v_add_f32_e32 v21, v54, v55
	ds_swizzle_b32 v54, v21 offset:swizzle(SWAP,1)
	s_waitcnt lgkmcnt(0)
	v_add_f32_e32 v21, v21, v54
	ds_swizzle_b32 v54, v21 offset:swizzle(SWAP,2)
	s_waitcnt lgkmcnt(0)
	v_add_f32_e32 v21, v21, v54
	ds_swizzle_b32 v54, v21 offset:swizzle(SWAP,4)
	s_waitcnt lgkmcnt(0)
	v_add_f32_e32 v21, v21, v54
	ds_swizzle_b32 v54, v21 offset:swizzle(SWAP,8)
	s_waitcnt lgkmcnt(0)
	v_add_f32_e32 v21, v21, v54
	ds_swizzle_b32 v54, v21 offset:swizzle(SWAP,16)
	s_waitcnt lgkmcnt(0)
	v_add_f32_e32 v21, v21, v54
	ds_bpermute_b32 v54, v20, v21
	s_waitcnt lgkmcnt(0)
; DI unsigned pk2(float lo, float hi) { unsigned r; asm("v_cvt_pk_bf16_f32 %0, %1, %2" : "=v"(r) : "v"(lo), "v"(hi)); return r; }
; DI void rms_row(const float* xrow, const float* g, u16* orow, int lane) {
;     ...
;   const float rstd = rsqrtf(wave_sum(s, lane) * (1.f / DM) + EPS);
;   u32x2* o8 = (u32x2*)orow + lane;
; #pragma unroll
;   for (int j = 0; j < 8; ++j) { const f32x4 gg = gr[64 * j]; u32x2 o; o.x = pk2(v[j].x * rstd * gg.x, v[j].y * rstd * gg.y); o.y = pk2(v[j].z * rstd * gg.z, v[j].w * rstd * gg.w); o8[64 * j] = o; }
	v_add_f32_e32 v21, v21, v54
	v_fmamk_f32 v21, v21, 0x3a000000, v234
	v_mul_f32_e32 v54, 0x4b800000, v21
	v_cmp_gt_f32_e32 vcc, s81, v21
	s_nop 1
	v_cndmask_b32_e32 v21, v21, v54, vcc
	v_rsq_f32_e32 v21, v21
	v_lshlrev_b64 v[54:55], 12, v[4:5]
	v_lshl_add_u64 v[54:55], v[10:11], 0, v[54:55]
	v_mul_f32_e32 v5, 0x45800000, v21
	v_cndmask_b32_e32 v5, v21, v5, vcc
	v_mul_f32_e32 v21, v22, v5
	v_mul_f32_e32 v22, v23, v5
	v_mul_f32_e32 v23, v24, v5
	v_mul_f32_e32 v24, v25, v5
	s_waitcnt vmcnt(7)
	v_mul_f32_e32 v22, v51, v22
	v_mul_f32_e32 v23, v52, v23
	v_mul_f32_e32 v21, v50, v21
	v_mul_f32_e32 v24, v53, v24
	v_cvt_pk_bf16_f32 v22, v21, v22
	v_cvt_pk_bf16_f32 v23, v23, v24
	global_store_dwordx2 v[54:55], v[22:23], off
	v_mul_f32_e32 v21, v26, v5
	v_mul_f32_e32 v26, v27, v5
	v_mul_f32_e32 v27, v28, v5
	v_mul_f32_e32 v28, v29, v5
	v_mul_f32_e32 v0, v0, v5
	v_mul_f32_e32 v1, v1, v5
	v_mul_f32_e32 v2, v2, v5
	v_mul_f32_e32 v3, v3, v5
	s_waitcnt vmcnt(7)
	v_mov_b32_e32 v22, v100
	v_mov_b32_e32 v23, v101
	v_mov_b32_e32 v24, v102
	v_mov_b32_e32 v25, v103
	v_mul_f32_e32 v21, v22, v21
	v_mul_f32_e32 v22, v23, v26
	v_mul_f32_e32 v23, v24, v27
	v_mul_f32_e32 v24, v25, v28
	v_cvt_pk_bf16_f32 v22, v21, v22
	v_cvt_pk_bf16_f32 v23, v23, v24
	global_store_dwordx2 v[54:55], v[22:23], off offset:512
	v_mul_f32_e32 v21, v30, v5
	v_mul_f32_e32 v26, v31, v5
	v_mul_f32_e32 v27, v32, v5
	v_mul_f32_e32 v28, v33, v5
	s_waitcnt vmcnt(7)
	v_mov_b32_e32 v22, v104
	v_mov_b32_e32 v23, v105
	v_mov_b32_e32 v24, v106
	v_mov_b32_e32 v25, v107
	v_mul_f32_e32 v21, v22, v21
	v_mul_f32_e32 v22, v23, v26
	v_mul_f32_e32 v23, v24, v27
	v_mul_f32_e32 v24, v25, v28
	v_cvt_pk_bf16_f32 v22, v21, v22
	v_cvt_pk_bf16_f32 v23, v23, v24
	global_store_dwordx2 v[54:55], v[22:23], off offset:1024
	v_mul_f32_e32 v21, v34, v5
	v_mul_f32_e32 v26, v35, v5
	v_mul_f32_e32 v27, v36, v5
	v_mul_f32_e32 v28, v37, v5
	s_waitcnt vmcnt(7)
	v_mov_b32_e32 v22, v108
	v_mov_b32_e32 v23, v109
	v_mov_b32_e32 v24, v110
	v_mov_b32_e32 v25, v111
	v_mul_f32_e32 v21, v21, v22
	v_mul_f32_e32 v22, v26, v23
	v_mul_f32_e32 v23, v27, v24
	v_mul_f32_e32 v24, v28, v25
	v_cvt_pk_bf16_f32 v22, v21, v22
	v_cvt_pk_bf16_f32 v23, v23, v24
	global_store_dwordx2 v[54:55], v[22:23], off offset:1536
	v_mul_f32_e32 v21, v38, v5
	v_mul_f32_e32 v26, v39, v5
	v_mul_f32_e32 v27, v40, v5
	v_mul_f32_e32 v28, v41, v5
	s_waitcnt vmcnt(7)
	v_mov_b32_e32 v22, v112
	v_mov_b32_e32 v23, v113
	v_mov_b32_e32 v24, v114
	v_mov_b32_e32 v25, v115
	v_mul_f32_e32 v21, v21, v22
	v_mul_f32_e32 v22, v26, v23
	v_mul_f32_e32 v23, v27, v24
	v_mul_f32_e32 v24, v28, v25
	v_cvt_pk_bf16_f32 v22, v21, v22
	v_cvt_pk_bf16_f32 v23, v23, v24
	global_store_dwordx2 v[54:55], v[22:23], off offset:2048
	v_mul_f32_e32 v21, v42, v5
	v_mul_f32_e32 v26, v43, v5
	v_mul_f32_e32 v27, v44, v5
	v_mul_f32_e32 v28, v45, v5
	s_waitcnt vmcnt(7)
	v_mov_b32_e32 v22, v116
	v_mov_b32_e32 v23, v117
	v_mov_b32_e32 v24, v118
	v_mov_b32_e32 v25, v119
	v_mul_f32_e32 v21, v21, v22
	v_mul_f32_e32 v22, v26, v23
	v_mul_f32_e32 v23, v27, v24
	v_mul_f32_e32 v24, v28, v25
	v_cvt_pk_bf16_f32 v22, v21, v22
	v_cvt_pk_bf16_f32 v23, v23, v24
	global_store_dwordx2 v[54:55], v[22:23], off offset:2560
	v_mul_f32_e32 v21, v46, v5
	v_mul_f32_e32 v26, v47, v5
	v_mul_f32_e32 v27, v48, v5
	v_mul_f32_e32 v28, v49, v5
	s_waitcnt vmcnt(7)
	v_mov_b32_e32 v22, v120
	v_mov_b32_e32 v23, v121
	v_mov_b32_e32 v24, v122
	v_mov_b32_e32 v25, v123
	v_mul_f32_e32 v21, v21, v22
	v_mul_f32_e32 v22, v26, v23
	v_mul_f32_e32 v23, v27, v24
	v_mul_f32_e32 v24, v28, v25
	v_cvt_pk_bf16_f32 v22, v21, v22
	v_cvt_pk_bf16_f32 v23, v23, v24
	global_store_dwordx2 v[54:55], v[22:23], off offset:3072
	s_waitcnt vmcnt(7)
	v_mov_b32_e32 v22, v124
	v_mov_b32_e32 v23, v125
	v_mov_b32_e32 v24, v126
	v_mov_b32_e32 v25, v127
	v_mul_f32_e32 v0, v0, v22
	v_mul_f32_e32 v1, v1, v23
	v_mul_f32_e32 v2, v2, v24
	v_mul_f32_e32 v3, v3, v25
	v_cvt_pk_bf16_f32 v0, v0, v1
	v_cvt_pk_bf16_f32 v1, v2, v3
	global_store_dwordx2 v[54:55], v[0:1], off offset:3584
	s_nop 0
	v_lshl_add_u32 v4, s0, 3, v4
	s_movk_i32 s0, 0x407f
	v_cmp_lt_i32_e32 vcc, s0, v4
	s_or_b64 s[10:11], vcc, s[10:11]
	s_andn2_b64 exec, exec, s[10:11]
	s_cbranch_execnz .LBB0_19

; DI unsigned pk2(float lo, float hi) { unsigned r; asm("v_cvt_pk_bf16_f32 %0, %1, %2" : "=v"(r) : "v"(lo), "v"(hi)); return r; }
; DI void unpack8(const u32x4 u, float* f) { f[0] = bflo(u.x); f[1] = bfhi(u.x); f[2] = bflo(u.y); f[3] = bfhi(u.y); f[4] = bflo(u.z); f[5] = bfhi(u.z); f[6] = bflo(u.w); f[7] = bfhi(u.w); }
; DI void load_q_frags(const u16* qrow, bool valid, const float* gain, bool norm, bf16x8* qf, int fq, int lane) {
;   float f[4][8];
; #pragma unroll
;   for (int ds = 0; ds < 4; ++ds) { u32x4 raw = {0u, 0u, 0u, 0u}; if (valid) raw = *(const u32x4*)(qrow + 32 * ds + 8 * fq); unpack8(raw, f[ds]); }
;   float sc = 0.08838834764831845f;
;   if (norm) {
;     float ss = 0.f;
; #pragma unroll
;     for (int ds = 0; ds < 4; ++ds)
; #pragma unroll
;       for (int e = 0; e < 8; ++e) ss += f[ds][e] * f[ds][e];
;     ss += shx<16>(ss, lane); ss += shx<32>(ss, lane);
;     sc *= rsqrtf(ss * (1.f / 128.f) + EPS);
;   }
; #pragma unroll
;   for (int ds = 0; ds < 4; ++ds) {
;     float gg[8];
;     if (norm) { const f32x4 a = *(const f32x4*)(gain + 32 * ds + 8 * fq), b = *(const f32x4*)(gain + 32 * ds + 8 * fq + 4);
;       gg[0] = a.x; gg[1] = a.y; gg[2] = a.z; gg[3] = a.w; gg[4] = b.x; gg[5] = b.y; gg[6] = b.z; gg[7] = b.w; }
;     else {
; #pragma unroll
;       for (int e = 0; e < 8; ++e) gg[e] = 1.f; }
;     u32x4 o; o.x = pk2(f[ds][0] * sc * gg[0], f[ds][1] * sc * gg[1]); o.y = pk2(f[ds][2] * sc * gg[2], f[ds][3] * sc * gg[3]);
;     o.z = pk2(f[ds][4] * sc * gg[4], f[ds][5] * sc * gg[5]); o.w = pk2(f[ds][6] * sc * gg[6], f[ds][7] * sc * gg[7]);
;     qf[ds] = __builtin_bit_cast(bf16x8, o);
;   }
; DI void mix_mem(CP& p, int l, int it, LAS unsigned char* lds) {
;     ...
;     const int rowq = rowq0 + qp * 128;
;     bf16x8 qf[4];
;     load_q_frags(proj + (size_t)rowq * NPROJ + C_MQ + hh * 128, true, p.in[20] + l * 128, true, qf, fq, lane);
.LBB0_268:
	v_add_u32_e32 v82, s4, v135
	v_mov_b64_e32 v[0:1], s[16:17]
	v_mad_i64_i32 v[0:1], s[4:5], v82, s92, v[0:1]
	v_lshl_add_u64 v[80:81], v[0:1], 0, s[38:39]
	v_lshl_add_u64 v[0:1], v[80:81], 0, v[146:147]
	s_mov_b64 s[4:5], 0x2800
	v_lshl_add_u64 v[12:13], v[0:1], 0, s[4:5]
	v_add_co_u32_e32 v0, vcc, 0x2000, v0
	global_load_dwordx4 v[20:23], v[12:13], off offset:192
	s_nop 0
	v_addc_co_u32_e32 v1, vcc, 0, v1, vcc
	global_load_dwordx4 v[0:3], v[0:1], off offset:2048
	global_load_dwordx4 v[164:167], v[12:13], off offset:64
	global_load_dwordx4 v[168:171], v[12:13], off offset:128
	v_add_co_u32_e32 v188, vcc, v80, v78
	s_nop 1
	v_addc_co_u32_e32 v189, vcc, 0, v81, vcc
	v_add_co_u32_e32 v188, vcc, 0x2c00, v188
	s_nop 1
	v_addc_co_u32_e32 v189, vcc, 0, v189, vcc
	global_load_dwordx2 v[172:173], v[188:189], off
	global_load_dwordx2 v[174:175], v[188:189], off offset:32
	global_load_dwordx2 v[176:177], v[188:189], off offset:64
	global_load_dwordx2 v[178:179], v[188:189], off offset:96
	global_load_dwordx2 v[180:181], v[188:189], off offset:128
	global_load_dwordx2 v[182:183], v[188:189], off offset:160
	global_load_dwordx2 v[184:185], v[188:189], off offset:192
	global_load_dwordx2 v[186:187], v[188:189], off offset:224
	s_mov_b32 s0, 0xf149f2ca
	v_ashrrev_i32_e32 v83, 31, v82
	s_and_b64 s[6:7], s[10:11], s[18:19]
	s_mov_b64 s[18:19], 0
	s_waitcnt vmcnt(11)
	v_and_b32_e32 v14, 0xffff0000, v21
	v_lshlrev_b32_e32 v15, 16, v21
	s_waitcnt vmcnt(10)
	v_lshlrev_b32_e32 v29, 16, v0
	v_and_b32_e32 v34, 0xffff0000, v0
	v_lshlrev_b32_e32 v35, 16, v1
	v_and_b32_e32 v36, 0xffff0000, v1
	v_lshlrev_b32_e32 v37, 16, v2
	v_and_b32_e32 v38, 0xffff0000, v2
	v_lshlrev_b32_e32 v39, 16, v3
	v_and_b32_e32 v40, 0xffff0000, v3
	s_waitcnt vmcnt(9)
	v_lshlrev_b32_e32 v27, 16, v164
	v_and_b32_e32 v8, 0xffff0000, v164
	v_lshlrev_b32_e32 v26, 16, v165
	v_and_b32_e32 v9, 0xffff0000, v165
	v_lshlrev_b32_e32 v25, 16, v166
	v_and_b32_e32 v10, 0xffff0000, v166
	v_lshlrev_b32_e32 v24, 16, v167
	v_and_b32_e32 v11, 0xffff0000, v167
	v_mul_f32_e32 v12, v34, v34
	v_fmac_f32_e32 v12, v29, v29
	v_fmac_f32_e32 v12, v35, v35
	v_fmac_f32_e32 v12, v36, v36
	v_fmac_f32_e32 v12, v37, v37
	v_fmac_f32_e32 v12, v38, v38
	v_fmac_f32_e32 v12, v39, v39
	v_fmac_f32_e32 v12, v40, v40
	v_fmac_f32_e32 v12, v27, v27
	v_fmac_f32_e32 v12, v8, v8
	v_fmac_f32_e32 v12, v26, v26
	v_fmac_f32_e32 v12, v9, v9
	v_fmac_f32_e32 v12, v25, v25
	v_fmac_f32_e32 v12, v10, v10
	v_fmac_f32_e32 v12, v24, v24
	v_fmac_f32_e32 v12, v11, v11
	s_waitcnt vmcnt(8)
	v_lshlrev_b32_e32 v19, 16, v168
	v_and_b32_e32 v4, 0xffff0000, v168
	v_fmac_f32_e32 v12, v19, v19
	v_lshlrev_b32_e32 v18, 16, v169
	v_fmac_f32_e32 v12, v4, v4
	v_and_b32_e32 v5, 0xffff0000, v169
	v_fmac_f32_e32 v12, v18, v18
	v_lshlrev_b32_e32 v17, 16, v170
	v_fmac_f32_e32 v12, v5, v5
	v_and_b32_e32 v6, 0xffff0000, v170
	v_fmac_f32_e32 v12, v17, v17
	v_lshlrev_b32_e32 v16, 16, v171
	v_fmac_f32_e32 v12, v6, v6
	v_and_b32_e32 v7, 0xffff0000, v171
	v_fmac_f32_e32 v12, v16, v16
	v_and_b32_e32 v0, 0xffff0000, v20
	v_lshlrev_b32_e32 v1, 16, v20
	v_fmac_f32_e32 v12, v7, v7
	v_pk_mul_f32 v[2:3], v[0:1], v[0:1]
	s_nop 0
	v_add_f32_e32 v3, v3, v12
	v_add_f32_e32 v12, v2, v3
	v_pk_mul_f32 v[2:3], v[14:15], v[14:15]
	s_nop 0
	v_add_f32_e32 v3, v3, v12
	v_add_f32_e32 v20, v2, v3
	v_and_b32_e32 v2, 0xffff0000, v22
	v_lshlrev_b32_e32 v3, 16, v22
	v_pk_mul_f32 v[12:13], v[2:3], v[2:3]
	s_nop 0
	v_add_f32_e32 v13, v13, v20
	v_add_f32_e32 v22, v12, v13
	v_and_b32_e32 v12, 0xffff0000, v23
	v_lshlrev_b32_e32 v13, 16, v23
	v_pk_mul_f32 v[20:21], v[12:13], v[12:13]
	s_nop 0
	v_add_f32_e32 v21, v21, v22
	v_add_f32_e32 v20, v20, v21
	ds_swizzle_b32 v21, v20 offset:swizzle(SWAP,16)
	s_waitcnt lgkmcnt(0)
	v_add_f32_e32 v20, v20, v21
	ds_bpermute_b32 v21, v136, v20
	s_waitcnt lgkmcnt(0)
	v_add_f32_e32 v20, v20, v21
	v_fmamk_f32 v20, v20, 0x3c000000, v234
	v_cmp_gt_f32_e32 vcc, s81, v20
	v_mul_f32_e32 v21, 0x4b800000, v20
	s_nop 0
	v_cndmask_b32_e32 v20, v20, v21, vcc
	v_rsq_f32_e32 v20, v20
	s_nop 0
	v_mul_f32_e32 v21, 0x45800000, v20
	v_cndmask_b32_e32 v20, v20, v21, vcc
	v_mul_f32_e32 v28, 0x3db504f3, v20
	global_load_dwordx4 v[30:33], v[76:77], off offset:16
	global_load_dwordx4 v[20:23], v[76:77], off
	v_mul_f32_e32 v29, v28, v29
	v_mul_f32_e32 v27, v28, v27
	v_mul_f32_e32 v8, v28, v8
	v_mul_f32_e32 v26, v28, v26
	v_mul_f32_e32 v9, v28, v9
	v_mul_f32_e32 v25, v28, v25
	v_mul_f32_e32 v10, v28, v10
	v_mul_f32_e32 v24, v28, v24
	v_mul_f32_e32 v11, v28, v11
	v_mul_f32_e32 v19, v28, v19
	v_mul_f32_e32 v4, v28, v4
	v_mul_f32_e32 v18, v28, v18
	v_mul_f32_e32 v5, v28, v5
	v_mul_f32_e32 v17, v28, v17
	v_mul_f32_e32 v6, v28, v6
	v_mul_f32_e32 v16, v28, v16
	v_mul_f32_e32 v7, v28, v7
	v_mul_f32_e32 v1, v28, v1
	v_mul_f32_e32 v0, v28, v0
	v_mul_f32_e32 v3, v28, v3
	v_mul_f32_e32 v2, v28, v2
	v_mul_f32_e32 v14, v28, v14
	v_mul_f32_e32 v12, v28, v12
	s_waitcnt vmcnt(0)
	v_mul_f32_e32 v20, v20, v29
	v_mul_f32_e32 v29, v28, v34
	v_mul_f32_e32 v21, v21, v29
	v_cvt_pk_bf16_f32 v20, v20, v21
	v_mul_f32_e32 v21, v28, v35
	v_mul_f32_e32 v21, v22, v21
	v_mul_f32_e32 v22, v28, v36
	v_mul_f32_e32 v22, v23, v22
	v_cvt_pk_bf16_f32 v21, v21, v22
	v_mul_f32_e32 v22, v28, v37
	v_mul_f32_e32 v23, v28, v38
	v_mul_f32_e32 v22, v30, v22
	v_mul_f32_e32 v23, v31, v23
	v_cvt_pk_bf16_f32 v22, v22, v23
	v_mul_f32_e32 v23, v28, v39
	v_mul_f32_e32 v29, v28, v40
	v_mul_f32_e32 v23, v32, v23
	v_mul_f32_e32 v29, v33, v29
	global_load_dwordx4 v[30:33], v[76:77], off offset:144
	global_load_dwordx4 v[34:37], v[76:77], off offset:128
	v_cvt_pk_bf16_f32 v23, v23, v29
	s_waitcnt vmcnt(1)
	v_mul_f32_e32 v25, v30, v25
	s_waitcnt vmcnt(0)
; #define LAS __attribute__((address_space(3)))
; DI unsigned pk2(float lo, float hi) { unsigned r; asm("v_cvt_pk_bf16_f32 %0, %1, %2" : "=v"(r) : "v"(lo), "v"(hi)); return r; }
; DI void load_q_frags(const u16* qrow, bool valid, const float* gain, bool norm, bf16x8* qf, int fq, int lane) {
;     ...
;     if (norm) { const f32x4 a = *(const f32x4*)(gain + 32 * ds + 8 * fq), b = *(const f32x4*)(gain + 32 * ds + 8 * fq + 4);
;       gg[0] = a.x; gg[1] = a.y; gg[2] = a.z; gg[3] = a.w; gg[4] = b.x; gg[5] = b.y; gg[6] = b.z; gg[7] = b.w; }
;     else {
; #pragma unroll
;       for (int e = 0; e < 8; ++e) gg[e] = 1.f; }
;     u32x4 o; o.x = pk2(f[ds][0] * sc * gg[0], f[ds][1] * sc * gg[1]); o.y = pk2(f[ds][2] * sc * gg[2], f[ds][3] * sc * gg[3]);
;     o.z = pk2(f[ds][4] * sc * gg[4], f[ds][5] * sc * gg[5]); o.w = pk2(f[ds][6] * sc * gg[6], f[ds][7] * sc * gg[7]);
;     qf[ds] = __builtin_bit_cast(bf16x8, o);
; DI void mix_mem(CP& p, int l, int it, LAS unsigned char* lds) {
;     ...
;     for (int kt = 0; kt < 16; ++kt) {
;       f32x4 a = {0.f, 0.f, 0.f, 0.f};
; #pragma unroll
;       for (int ds = 0; ds < 4; ++ds) {
;         const bf16x8 kf = *(const LAS bf16x8*)(kbuf + (16 * kt + fr) * KSTR + 32 * ds + 8 * fq);
;         a = __builtin_amdgcn_mfma_f32_16x16x32_bf16(kf, qf[ds], a, 0, 0, 0);
;       }
;       sc[kt] = a;
;     }
	v_mul_f32_e32 v27, v34, v27
	v_mul_f32_e32 v8, v35, v8
	v_mul_f32_e32 v26, v36, v26
	v_mul_f32_e32 v9, v37, v9
	v_mul_f32_e32 v10, v31, v10
	v_mul_f32_e32 v24, v32, v24
	v_mul_f32_e32 v11, v33, v11
	v_cvt_pk_bf16_f32 v8, v27, v8
	v_cvt_pk_bf16_f32 v9, v26, v9
	v_cvt_pk_bf16_f32 v10, v25, v10
	v_cvt_pk_bf16_f32 v11, v24, v11
	global_load_dwordx4 v[24:27], v[76:77], off offset:272
	global_load_dwordx4 v[30:33], v[76:77], off offset:256
	s_waitcnt vmcnt(1)
	v_mul_f32_e32 v17, v24, v17
	s_waitcnt vmcnt(0)
	v_mul_f32_e32 v19, v30, v19
	v_mul_f32_e32 v4, v31, v4
	v_mul_f32_e32 v18, v32, v18
	v_mul_f32_e32 v5, v33, v5
	v_mul_f32_e32 v6, v25, v6
	v_mul_f32_e32 v16, v26, v16
	v_mul_f32_e32 v7, v27, v7
	v_cvt_pk_bf16_f32 v4, v19, v4
	v_cvt_pk_bf16_f32 v5, v18, v5
	v_cvt_pk_bf16_f32 v6, v17, v6
	v_cvt_pk_bf16_f32 v7, v16, v7
	global_load_dwordx4 v[16:19], v[76:77], off offset:400
	global_load_dwordx4 v[24:27], v[76:77], off offset:384
	ds_read_b128 v[32:35], v137 offset:13120
	ds_read_b128 v[36:39], v137 offset:17472
	ds_read_b128 v[40:43], v137 offset:21824
	ds_read_b128 v[44:47], v137 offset:26176
	ds_read_b128 v[48:51], v137 offset:30528
	ds_read_b128 v[52:55], v137 offset:34880
	ds_read_b128 v[56:59], v137 offset:39232
	ds_read_b128 v[60:63], v137 offset:43584
	ds_read_b128 v[64:67], v137 offset:47936
	ds_read_b128 v[68:71], v137 offset:52288
	ds_read_b128 v[72:75], v137 offset:56640
	ds_read_b128 v[84:87], v137 offset:60992
	s_waitcnt vmcnt(1)
	v_mul_f32_e32 v3, v16, v3
	s_waitcnt vmcnt(0)
	v_mul_f32_e32 v1, v24, v1
	v_mul_f32_e32 v0, v25, v0
	v_mul_f32_e32 v2, v17, v2
	v_cvt_pk_bf16_f32 v0, v1, v0
	v_mul_f32_e32 v1, v28, v15
	v_cvt_pk_bf16_f32 v2, v3, v2
	v_mul_f32_e32 v3, v28, v13
	v_mul_f32_e32 v1, v26, v1
	v_mul_f32_e32 v14, v27, v14
	v_mul_f32_e32 v3, v18, v3
	v_mul_f32_e32 v12, v19, v12
	v_cvt_pk_bf16_f32 v1, v1, v14
	v_cvt_pk_bf16_f32 v3, v3, v12
	ds_read_b128 v[12:15], v137
	ds_read_b128 v[16:19], v137 offset:64
	s_waitcnt lgkmcnt(1)
	v_mfma_f32_16x16x32_bf16 v[12:15], v[12:15], v[20:23], 0
	ds_read_b128 v[24:27], v137 offset:4416
	ds_read_b128 v[28:31], v137 offset:8768
	s_waitcnt lgkmcnt(2)
	v_mfma_f32_16x16x32_bf16 v[12:15], v[16:19], v[8:11], v[12:15]
	ds_read_b128 v[16:19], v137 offset:128
	s_waitcnt lgkmcnt(0)
	v_mfma_f32_16x16x32_bf16 v[12:15], v[16:19], v[4:7], v[12:15]
	ds_read_b128 v[16:19], v137 offset:192
	s_waitcnt lgkmcnt(0)
	v_mfma_f32_16x16x32_bf16 v[12:15], v[16:19], v[0:3], v[12:15]
	ds_read_b128 v[16:19], v137 offset:4352
	s_waitcnt lgkmcnt(0)
	v_mfma_f32_16x16x32_bf16 v[16:19], v[16:19], v[20:23], 0
	v_mfma_f32_16x16x32_bf16 v[16:19], v[24:27], v[8:11], v[16:19]
	ds_read_b128 v[24:27], v137 offset:4480
	s_waitcnt lgkmcnt(0)
	v_mfma_f32_16x16x32_bf16 v[16:19], v[24:27], v[4:7], v[16:19]
	ds_read_b128 v[24:27], v137 offset:4544
	s_waitcnt lgkmcnt(0)
	v_mfma_f32_16x16x32_bf16 v[16:19], v[24:27], v[0:3], v[16:19]
	ds_read_b128 v[24:27], v137 offset:8704
	s_waitcnt lgkmcnt(0)
	v_mfma_f32_16x16x32_bf16 v[24:27], v[24:27], v[20:23], 0
	v_mfma_f32_16x16x32_bf16 v[24:27], v[28:31], v[8:11], v[24:27]
	ds_read_b128 v[28:31], v137 offset:8832
	s_waitcnt lgkmcnt(0)
	v_mfma_f32_16x16x32_bf16 v[24:27], v[28:31], v[4:7], v[24:27]
	ds_read_b128 v[28:31], v137 offset:8896
	s_waitcnt lgkmcnt(0)
	v_mfma_f32_16x16x32_bf16 v[24:27], v[28:31], v[0:3], v[24:27]
	ds_read_b128 v[28:31], v137 offset:13056
	s_waitcnt lgkmcnt(0)
	v_mfma_f32_16x16x32_bf16 v[28:31], v[28:31], v[20:23], 0
	v_mfma_f32_16x16x32_bf16 v[28:31], v[32:35], v[8:11], v[28:31]
	ds_read_b128 v[32:35], v137 offset:13184
	s_waitcnt lgkmcnt(0)
	v_mfma_f32_16x16x32_bf16 v[28:31], v[32:35], v[4:7], v[28:31]
	ds_read_b128 v[32:35], v137 offset:13248
	s_waitcnt lgkmcnt(0)
	v_mfma_f32_16x16x32_bf16 v[28:31], v[32:35], v[0:3], v[28:31]
	ds_read_b128 v[32:35], v137 offset:17408
	s_waitcnt lgkmcnt(0)
	v_mfma_f32_16x16x32_bf16 v[32:35], v[32:35], v[20:23], 0
	v_mfma_f32_16x16x32_bf16 v[32:35], v[36:39], v[8:11], v[32:35]
	ds_read_b128 v[36:39], v137 offset:17536
	s_waitcnt lgkmcnt(0)
	v_mfma_f32_16x16x32_bf16 v[32:35], v[36:39], v[4:7], v[32:35]
	ds_read_b128 v[36:39], v137 offset:17600
	s_waitcnt lgkmcnt(0)
	v_mfma_f32_16x16x32_bf16 v[32:35], v[36:39], v[0:3], v[32:35]
	ds_read_b128 v[36:39], v137 offset:21760
	s_waitcnt lgkmcnt(0)
	v_mfma_f32_16x16x32_bf16 v[36:39], v[36:39], v[20:23], 0
	v_mfma_f32_16x16x32_bf16 v[36:39], v[40:43], v[8:11], v[36:39]
	ds_read_b128 v[40:43], v137 offset:21888
	s_waitcnt lgkmcnt(0)
	v_mfma_f32_16x16x32_bf16 v[36:39], v[40:43], v[4:7], v[36:39]
	ds_read_b128 v[40:43], v137 offset:21952
	s_waitcnt lgkmcnt(0)
	v_mfma_f32_16x16x32_bf16 v[36:39], v[40:43], v[0:3], v[36:39]
	ds_read_b128 v[40:43], v137 offset:26112
	s_waitcnt lgkmcnt(0)
	v_mfma_f32_16x16x32_bf16 v[40:43], v[40:43], v[20:23], 0
	v_mfma_f32_16x16x32_bf16 v[40:43], v[44:47], v[8:11], v[40:43]
	ds_read_b128 v[44:47], v137 offset:26240
	s_waitcnt lgkmcnt(0)
	v_mfma_f32_16x16x32_bf16 v[40:43], v[44:47], v[4:7], v[40:43]
	ds_read_b128 v[44:47], v137 offset:26304
	s_waitcnt lgkmcnt(0)
	v_mfma_f32_16x16x32_bf16 v[40:43], v[44:47], v[0:3], v[40:43]
	ds_read_b128 v[44:47], v137 offset:30464
	s_waitcnt lgkmcnt(0)
	v_mfma_f32_16x16x32_bf16 v[44:47], v[44:47], v[20:23], 0
	v_mfma_f32_16x16x32_bf16 v[44:47], v[48:51], v[8:11], v[44:47]
	ds_read_b128 v[48:51], v137 offset:30592
	s_waitcnt lgkmcnt(0)
	v_mfma_f32_16x16x32_bf16 v[44:47], v[48:51], v[4:7], v[44:47]
	ds_read_b128 v[48:51], v137 offset:30656
	s_waitcnt lgkmcnt(0)
	v_mfma_f32_16x16x32_bf16 v[44:47], v[48:51], v[0:3], v[44:47]
	ds_read_b128 v[48:51], v137 offset:34816
	s_waitcnt lgkmcnt(0)
; #define LAS __attribute__((address_space(3)))
; DI void mix_mem(CP& p, int l, int it, LAS unsigned char* lds) {
;     ...
;     for (int kt = 0; kt < 16; ++kt) {
;       f32x4 a = {0.f, 0.f, 0.f, 0.f};
; #pragma unroll
;       for (int ds = 0; ds < 4; ++ds) {
;         const bf16x8 kf = *(const LAS bf16x8*)(kbuf + (16 * kt + fr) * KSTR + 32 * ds + 8 * fq);
;         a = __builtin_amdgcn_mfma_f32_16x16x32_bf16(kf, qf[ds], a, 0, 0, 0);
;       }
;       sc[kt] = a;
;     }
;     float mx = -1e30f;
; #pragma unroll
;     for (int kt = 0; kt < 16; ++kt) mx = fmaxf(mx, fmaxf(fmaxf(sc[kt].x, sc[kt].y), fmaxf(sc[kt].z, sc[kt].w)));
;     mx = fmaxf(mx, shx<16>(mx, lane)); mx = fmaxf(mx, shx<32>(mx, lane));
	v_mfma_f32_16x16x32_bf16 v[48:51], v[48:51], v[20:23], 0
	v_mfma_f32_16x16x32_bf16 v[48:51], v[52:55], v[8:11], v[48:51]
	ds_read_b128 v[52:55], v137 offset:34944
	s_waitcnt lgkmcnt(0)
	v_mfma_f32_16x16x32_bf16 v[48:51], v[52:55], v[4:7], v[48:51]
	ds_read_b128 v[52:55], v137 offset:35008
	s_waitcnt lgkmcnt(0)
	v_mfma_f32_16x16x32_bf16 v[48:51], v[52:55], v[0:3], v[48:51]
	ds_read_b128 v[52:55], v137 offset:39168
	s_waitcnt lgkmcnt(0)
	v_mfma_f32_16x16x32_bf16 v[52:55], v[52:55], v[20:23], 0
	v_mfma_f32_16x16x32_bf16 v[52:55], v[56:59], v[8:11], v[52:55]
	ds_read_b128 v[56:59], v137 offset:39296
	s_waitcnt lgkmcnt(0)
	v_mfma_f32_16x16x32_bf16 v[52:55], v[56:59], v[4:7], v[52:55]
	ds_read_b128 v[56:59], v137 offset:39360
	s_waitcnt lgkmcnt(0)
	v_mfma_f32_16x16x32_bf16 v[52:55], v[56:59], v[0:3], v[52:55]
	ds_read_b128 v[56:59], v137 offset:43520
	s_waitcnt lgkmcnt(0)
	v_mfma_f32_16x16x32_bf16 v[56:59], v[56:59], v[20:23], 0
	v_mfma_f32_16x16x32_bf16 v[56:59], v[60:63], v[8:11], v[56:59]
	ds_read_b128 v[60:63], v137 offset:43648
	s_waitcnt lgkmcnt(0)
	v_mfma_f32_16x16x32_bf16 v[56:59], v[60:63], v[4:7], v[56:59]
	ds_read_b128 v[60:63], v137 offset:43712
	s_waitcnt lgkmcnt(0)
	v_mfma_f32_16x16x32_bf16 v[56:59], v[60:63], v[0:3], v[56:59]
	ds_read_b128 v[60:63], v137 offset:47872
	s_waitcnt lgkmcnt(0)
	v_mfma_f32_16x16x32_bf16 v[60:63], v[60:63], v[20:23], 0
	v_mfma_f32_16x16x32_bf16 v[60:63], v[64:67], v[8:11], v[60:63]
	ds_read_b128 v[64:67], v137 offset:48000
	s_waitcnt lgkmcnt(0)
	v_mfma_f32_16x16x32_bf16 v[60:63], v[64:67], v[4:7], v[60:63]
	ds_read_b128 v[64:67], v137 offset:48064
	s_waitcnt lgkmcnt(0)
	v_mfma_f32_16x16x32_bf16 v[60:63], v[64:67], v[0:3], v[60:63]
	ds_read_b128 v[64:67], v137 offset:52224
	s_waitcnt lgkmcnt(0)
	v_mfma_f32_16x16x32_bf16 v[64:67], v[64:67], v[20:23], 0
	v_mfma_f32_16x16x32_bf16 v[64:67], v[68:71], v[8:11], v[64:67]
	ds_read_b128 v[68:71], v137 offset:52352
	s_waitcnt lgkmcnt(0)
	v_mfma_f32_16x16x32_bf16 v[64:67], v[68:71], v[4:7], v[64:67]
	ds_read_b128 v[68:71], v137 offset:52416
	s_waitcnt lgkmcnt(0)
	v_mfma_f32_16x16x32_bf16 v[64:67], v[68:71], v[0:3], v[64:67]
	ds_read_b128 v[68:71], v137 offset:56576
	s_waitcnt lgkmcnt(0)
	v_mfma_f32_16x16x32_bf16 v[68:71], v[68:71], v[20:23], 0
	v_mfma_f32_16x16x32_bf16 v[68:71], v[72:75], v[8:11], v[68:71]
	ds_read_b128 v[72:75], v137 offset:56704
	s_waitcnt lgkmcnt(0)
	v_mfma_f32_16x16x32_bf16 v[68:71], v[72:75], v[4:7], v[68:71]
	ds_read_b128 v[72:75], v137 offset:56768
	s_waitcnt lgkmcnt(0)
	v_mfma_f32_16x16x32_bf16 v[68:71], v[72:75], v[0:3], v[68:71]
	ds_read_b128 v[72:75], v137 offset:60928
	s_waitcnt lgkmcnt(0)
	v_mfma_f32_16x16x32_bf16 v[72:75], v[72:75], v[20:23], 0
	v_mfma_f32_16x16x32_bf16 v[72:75], v[84:87], v[8:11], v[72:75]
	ds_read_b128 v[84:87], v137 offset:61056
	s_waitcnt lgkmcnt(0)
	v_mfma_f32_16x16x32_bf16 v[72:75], v[84:87], v[4:7], v[72:75]
	ds_read_b128 v[84:87], v137 offset:61120
	s_waitcnt lgkmcnt(0)
	v_mfma_f32_16x16x32_bf16 v[72:75], v[84:87], v[0:3], v[72:75]
	ds_read_b128 v[84:87], v137 offset:65280
	s_waitcnt lgkmcnt(0)
	v_mfma_f32_16x16x32_bf16 v[20:23], v[84:87], v[20:23], 0
	ds_read_b128 v[84:87], v137 offset:65344
	s_waitcnt lgkmcnt(0)
	v_mfma_f32_16x16x32_bf16 v[8:11], v[84:87], v[8:11], v[20:23]
	s_nop 4
	ds_read_b128 v[20:23], v137 offset:65408
	s_waitcnt lgkmcnt(0)
	v_mfma_f32_16x16x32_bf16 v[4:7], v[20:23], v[4:7], v[8:11]
	s_nop 2
	ds_read_b128 v[8:11], v137 offset:65472
	s_waitcnt lgkmcnt(0)
	v_mfma_f32_16x16x32_bf16 v[0:3], v[8:11], v[0:3], v[4:7]
	s_nop 2
	v_max_f32_e32 v4, v15, v15
	v_max_f32_e32 v5, v14, v14
	v_max_f32_e32 v4, v5, v4
	v_max_f32_e32 v5, v19, v19
	v_max_f32_e32 v6, v18, v18
	v_max_f32_e32 v5, v6, v5
	v_max3_f32 v4, v12, v13, v4
	v_max3_f32 v5, v16, v17, v5
	v_max3_f32 v4, v4, s0, v5
	v_max_f32_e32 v5, v27, v27
	v_max_f32_e32 v6, v26, v26
	v_max_f32_e32 v5, v6, v5
	v_max_f32_e32 v6, v31, v31
	v_max_f32_e32 v7, v30, v30
	v_max_f32_e32 v6, v7, v6
	v_max3_f32 v5, v24, v25, v5
	v_max3_f32 v6, v28, v29, v6
	v_max3_f32 v4, v4, v5, v6
	v_max_f32_e32 v5, v35, v35
	v_max_f32_e32 v6, v34, v34
	v_max_f32_e32 v5, v6, v5
	v_max_f32_e32 v6, v39, v39
	v_max_f32_e32 v7, v38, v38
	v_max_f32_e32 v6, v7, v6
	v_max3_f32 v5, v32, v33, v5
	v_max3_f32 v6, v36, v37, v6
	v_max3_f32 v4, v4, v5, v6
	v_max_f32_e32 v5, v43, v43
	v_max_f32_e32 v6, v42, v42
	v_max_f32_e32 v5, v6, v5
	v_max_f32_e32 v6, v47, v47
	v_max_f32_e32 v7, v46, v46
	v_max_f32_e32 v6, v7, v6
	v_max3_f32 v5, v40, v41, v5
	v_max3_f32 v6, v44, v45, v6
	v_max3_f32 v4, v4, v5, v6
	v_max_f32_e32 v5, v51, v51
	v_max_f32_e32 v6, v50, v50
	v_max_f32_e32 v5, v6, v5
	v_max_f32_e32 v6, v55, v55
	v_max_f32_e32 v7, v54, v54
	v_max_f32_e32 v6, v7, v6
	v_max3_f32 v5, v48, v49, v5
	v_max3_f32 v6, v52, v53, v6
	v_max3_f32 v4, v4, v5, v6
	v_max_f32_e32 v5, v59, v59
	v_max_f32_e32 v6, v58, v58
	v_max_f32_e32 v5, v6, v5
	v_max_f32_e32 v6, v63, v63
	v_max_f32_e32 v7, v62, v62
	v_max_f32_e32 v6, v7, v6
	v_max3_f32 v5, v56, v57, v5
	v_max3_f32 v6, v60, v61, v6
	v_max3_f32 v4, v4, v5, v6
	v_max_f32_e32 v5, v67, v67
	v_max_f32_e32 v6, v66, v66
	v_max_f32_e32 v5, v6, v5
	v_max_f32_e32 v6, v71, v71
	v_max_f32_e32 v7, v70, v70
	v_max_f32_e32 v6, v7, v6
	v_max3_f32 v5, v64, v65, v5
	v_max3_f32 v6, v68, v69, v6
	v_max3_f32 v4, v4, v5, v6
	v_max_f32_e32 v5, v75, v75
	v_max_f32_e32 v6, v74, v74
	v_max_f32_e32 v5, v6, v5
	v_max_f32_e32 v6, v3, v3
	v_max_f32_e32 v7, v2, v2
	v_max_f32_e32 v6, v7, v6
	v_max3_f32 v5, v72, v73, v5
	v_max3_f32 v6, v0, v1, v6
	v_max3_f32 v4, v4, v5, v6
	ds_swizzle_b32 v5, v4 offset:swizzle(SWAP,16)
	s_waitcnt lgkmcnt(0)
; DI void mix_mem(CP& p, int l, int it, LAS unsigned char* lds) {
;     ...
;     mx = fmaxf(mx, shx<16>(mx, lane)); mx = fmaxf(mx, shx<32>(mx, lane));
;     float sum = 0.f;
; #pragma unroll
;     for (int kt = 0; kt < 16; ++kt) { sc[kt].x = __expf(sc[kt].x - mx); sc[kt].y = __expf(sc[kt].y - mx); sc[kt].z = __expf(sc[kt].z - mx); sc[kt].w = __expf(sc[kt].w - mx);
;       sum += (sc[kt].x + sc[kt].y) + (sc[kt].z + sc[kt].w); }
;     sum += shx<16>(sum, lane); sum += shx<32>(sum, lane);
	v_max_f32_e32 v5, v5, v5
	v_max_f32_e32 v4, v4, v5
	ds_bpermute_b32 v5, v136, v4
	s_waitcnt lgkmcnt(0)
	v_max_f32_e32 v5, v5, v5
	v_max_f32_e32 v20, v4, v5
	v_sub_f32_e32 v5, v13, v20
	v_mul_f32_e32 v5, 0x3fb8aa3b, v5
	v_sub_f32_e32 v4, v12, v20
	v_exp_f32_e32 v6, v5
	v_sub_f32_e32 v5, v14, v20
	v_sub_f32_e32 v7, v15, v20
	v_mul_f32_e32 v4, 0x3fb8aa3b, v4
	v_mul_f32_e32 v5, 0x3fb8aa3b, v5
	v_mul_f32_e32 v7, 0x3fb8aa3b, v7
	v_exp_f32_e32 v4, v4
	v_exp_f32_e32 v5, v5
	v_exp_f32_e32 v7, v7
	v_sub_f32_e32 v11, v19, v20
	v_mul_f32_e32 v11, 0x3fb8aa3b, v11
	v_exp_f32_e32 v11, v11
	v_pk_add_f32 v[8:9], v[4:5], v[6:7]
	v_sub_f32_e32 v0, v0, v20
	v_add_f32_e32 v8, v8, v9
	v_sub_f32_e32 v9, v17, v20
	v_mul_f32_e32 v9, 0x3fb8aa3b, v9
	v_add_f32_e32 v127, 0, v8
	v_sub_f32_e32 v8, v16, v20
	v_exp_f32_e32 v10, v9
	v_sub_f32_e32 v9, v18, v20
	v_mul_f32_e32 v8, 0x3fb8aa3b, v8
	v_mul_f32_e32 v9, 0x3fb8aa3b, v9
	v_exp_f32_e32 v8, v8
	v_exp_f32_e32 v9, v9
	v_mul_f32_e32 v0, 0x3fb8aa3b, v0
	v_pk_add_f32 v[12:13], v[8:9], v[10:11]
	s_nop 0
	v_pk_add_f32 v[128:129], v[12:13], v[12:13] op_sel_hi:[0,1]
	v_sub_f32_e32 v12, v24, v20
	v_mul_f32_e32 v12, 0x3fb8aa3b, v12
	v_exp_f32_e32 v158, v12
	v_sub_f32_e32 v12, v25, v20
	v_mul_f32_e32 v12, 0x3fb8aa3b, v12
	v_exp_f32_e32 v159, v12
	v_sub_f32_e32 v12, v26, v20
	v_mul_f32_e32 v12, 0x3fb8aa3b, v12
	v_exp_f32_e32 v160, v12
	v_sub_f32_e32 v12, v27, v20
	v_mul_f32_e32 v12, 0x3fb8aa3b, v12
	v_exp_f32_e32 v161, v12
	v_sub_f32_e32 v12, v28, v20
	v_mul_f32_e32 v12, 0x3fb8aa3b, v12
	v_exp_f32_e32 v132, v12
	v_sub_f32_e32 v12, v29, v20
	v_mul_f32_e32 v12, 0x3fb8aa3b, v12
	v_exp_f32_e32 v130, v12
	v_sub_f32_e32 v12, v30, v20
	v_mul_f32_e32 v12, 0x3fb8aa3b, v12
	v_exp_f32_e32 v128, v12
	v_sub_f32_e32 v12, v31, v20
	v_mul_f32_e32 v12, 0x3fb8aa3b, v12
	v_exp_f32_e32 v126, v12
	v_add_f32_e32 v133, v158, v159
	v_add_f32_e32 v131, v160, v161
	v_pk_add_f32 v[12:13], v[132:133], v[130:131]
	v_pk_add_f32 v[14:15], v[128:129], v[126:127]
	s_nop 0
	v_pk_add_f32 v[12:13], v[12:13], v[14:15]
	s_nop 0
	v_pk_add_f32 v[110:111], v[12:13], v[12:13] op_sel_hi:[0,1]
	v_sub_f32_e32 v12, v32, v20
	v_mul_f32_e32 v12, 0x3fb8aa3b, v12
	v_exp_f32_e32 v122, v12
	v_sub_f32_e32 v12, v33, v20
	v_mul_f32_e32 v12, 0x3fb8aa3b, v12
	v_exp_f32_e32 v124, v12
	v_sub_f32_e32 v12, v34, v20
	v_mul_f32_e32 v12, 0x3fb8aa3b, v12
	v_exp_f32_e32 v123, v12
	v_sub_f32_e32 v12, v35, v20
	v_mul_f32_e32 v12, 0x3fb8aa3b, v12
	v_exp_f32_e32 v125, v12
	s_nop 0
	v_pk_add_f32 v[12:13], v[122:123], v[124:125]
	s_nop 0
	v_pk_add_f32 v[112:113], v[12:13], v[12:13] op_sel_hi:[0,1]
	v_sub_f32_e32 v12, v36, v20
	v_mul_f32_e32 v12, 0x3fb8aa3b, v12
	v_exp_f32_e32 v127, v12
	v_sub_f32_e32 v12, v37, v20
	v_mul_f32_e32 v12, 0x3fb8aa3b, v12
	v_exp_f32_e32 v129, v12
	v_sub_f32_e32 v12, v38, v20
	v_mul_f32_e32 v12, 0x3fb8aa3b, v12
	v_exp_f32_e32 v131, v12
	v_sub_f32_e32 v12, v39, v20
	v_mul_f32_e32 v12, 0x3fb8aa3b, v12
	v_exp_f32_e32 v133, v12
	v_sub_f32_e32 v12, v40, v20
	v_mul_f32_e32 v12, 0x3fb8aa3b, v12
	v_exp_f32_e32 v116, v12
	v_sub_f32_e32 v12, v41, v20
	v_mul_f32_e32 v12, 0x3fb8aa3b, v12
	v_exp_f32_e32 v114, v12
	v_sub_f32_e32 v12, v42, v20
	v_mul_f32_e32 v12, 0x3fb8aa3b, v12
	v_exp_f32_e32 v112, v12
	v_sub_f32_e32 v12, v43, v20
	v_mul_f32_e32 v12, 0x3fb8aa3b, v12
	v_exp_f32_e32 v110, v12
	v_add_f32_e32 v117, v127, v129
	v_add_f32_e32 v115, v131, v133
	v_pk_add_f32 v[12:13], v[116:117], v[114:115]
	v_pk_add_f32 v[14:15], v[112:113], v[110:111]
	s_nop 0
	v_pk_add_f32 v[12:13], v[12:13], v[14:15]
	s_nop 0
	v_pk_add_f32 v[102:103], v[12:13], v[12:13] op_sel_hi:[0,1]
	v_sub_f32_e32 v12, v44, v20
	v_mul_f32_e32 v12, 0x3fb8aa3b, v12
	v_exp_f32_e32 v118, v12
	v_sub_f32_e32 v12, v45, v20
	v_mul_f32_e32 v12, 0x3fb8aa3b, v12
	v_exp_f32_e32 v120, v12
	v_sub_f32_e32 v12, v46, v20
	v_mul_f32_e32 v12, 0x3fb8aa3b, v12
	v_exp_f32_e32 v119, v12
	v_sub_f32_e32 v12, v47, v20
	v_mul_f32_e32 v12, 0x3fb8aa3b, v12
	v_exp_f32_e32 v121, v12
	s_nop 0
	v_pk_add_f32 v[12:13], v[118:119], v[120:121]
	s_nop 0
	v_pk_add_f32 v[104:105], v[12:13], v[12:13] op_sel_hi:[0,1]
	v_sub_f32_e32 v12, v48, v20
	v_mul_f32_e32 v12, 0x3fb8aa3b, v12
	v_exp_f32_e32 v111, v12
	v_sub_f32_e32 v12, v49, v20
	v_mul_f32_e32 v12, 0x3fb8aa3b, v12
	v_exp_f32_e32 v113, v12
	v_sub_f32_e32 v12, v50, v20
	v_mul_f32_e32 v12, 0x3fb8aa3b, v12
	v_exp_f32_e32 v115, v12
	v_sub_f32_e32 v12, v51, v20
	v_mul_f32_e32 v12, 0x3fb8aa3b, v12
	v_exp_f32_e32 v117, v12
	v_sub_f32_e32 v12, v52, v20
	v_mul_f32_e32 v12, 0x3fb8aa3b, v12
	v_exp_f32_e32 v108, v12
	v_sub_f32_e32 v12, v53, v20
	v_mul_f32_e32 v12, 0x3fb8aa3b, v12
	v_exp_f32_e32 v106, v12
	v_sub_f32_e32 v12, v54, v20
	v_mul_f32_e32 v12, 0x3fb8aa3b, v12
	v_exp_f32_e32 v104, v12
	v_sub_f32_e32 v12, v55, v20
	v_mul_f32_e32 v12, 0x3fb8aa3b, v12
	v_exp_f32_e32 v102, v12
	v_add_f32_e32 v109, v111, v113
	v_add_f32_e32 v107, v115, v117
	v_pk_add_f32 v[12:13], v[108:109], v[106:107]
	v_pk_add_f32 v[14:15], v[104:105], v[102:103]
	s_nop 0
	v_pk_add_f32 v[12:13], v[12:13], v[14:15]
	s_nop 0
	v_pk_add_f32 v[86:87], v[12:13], v[12:13] op_sel_hi:[0,1]
	v_sub_f32_e32 v12, v56, v20
	v_mul_f32_e32 v12, 0x3fb8aa3b, v12
	v_exp_f32_e32 v96, v12
	v_sub_f32_e32 v12, v57, v20
	v_mul_f32_e32 v12, 0x3fb8aa3b, v12
	v_exp_f32_e32 v100, v12
	v_sub_f32_e32 v12, v58, v20
	v_mul_f32_e32 v12, 0x3fb8aa3b, v12
	v_exp_f32_e32 v97, v12
	v_sub_f32_e32 v12, v59, v20
	v_mul_f32_e32 v12, 0x3fb8aa3b, v12
	v_exp_f32_e32 v101, v12
	s_nop 0
	v_pk_add_f32 v[12:13], v[96:97], v[100:101]
	s_nop 0
	v_pk_add_f32 v[88:89], v[12:13], v[12:13] op_sel_hi:[0,1]
	v_sub_f32_e32 v12, v60, v20
	v_mul_f32_e32 v12, 0x3fb8aa3b, v12
	v_exp_f32_e32 v103, v12
; #define LAS __attribute__((address_space(3)))
; DI void gather_v8(const LAS u16* vb, int s, int fr, int fq, bf16x8* vf) {
;   const int q = fr >> 2, pp = fr & 3;
;   const unsigned a0 = (unsigned)(unsigned long)(vb + (32 * s + 4 * fq + q) * VSTR2) + 8u * pp;
;   const unsigned a1 = a0 + 16u * VSTR2 * 2u;
;   u32x2 lo[8], hi[8];
;   asm volatile("ds_read_b64_tr_b16 %0, %8\n\tds_read_b64_tr_b16 %1, %8 offset:32\n\tds_read_b64_tr_b16 %2, %8 offset:64\n\tds_read_b64_tr_b16 %3, %8 offset:96\n\t"
;                "ds_read_b64_tr_b16 %4, %8 offset:128\n\tds_read_b64_tr_b16 %5, %8 offset:160\n\tds_read_b64_tr_b16 %6, %8 offset:192\n\tds_read_b64_tr_b16 %7, %8 offset:224"
;                : "=&v"(lo[0]), "=&v"(lo[1]), "=&v"(lo[2]), "=&v"(lo[3]), "=&v"(lo[4]), "=&v"(lo[5]), "=&v"(lo[6]), "=&v"(lo[7]) : "v"(a0) : "memory");
;   asm volatile("ds_read_b64_tr_b16 %0, %16\n\tds_read_b64_tr_b16 %1, %16 offset:32\n\tds_read_b64_tr_b16 %2, %16 offset:64\n\tds_read_b64_tr_b16 %3, %16 offset:96\n\t"
;                "ds_read_b64_tr_b16 %4, %16 offset:128\n\tds_read_b64_tr_b16 %5, %16 offset:160\n\tds_read_b64_tr_b16 %6, %16 offset:192\n\tds_read_b64_tr_b16 %7, %16 offset:224\n\t"
;                "s_waitcnt lgkmcnt(0)"
;                : "=&v"(hi[0]), "=&v"(hi[1]), "=&v"(hi[2]), "=&v"(hi[3]), "=&v"(hi[4]), "=&v"(hi[5]), "=&v"(hi[6]), "=&v"(hi[7]),
;                  "+v"(lo[0]), "+v"(lo[1]), "+v"(lo[2]), "+v"(lo[3]), "+v"(lo[4]), "+v"(lo[5]), "+v"(lo[6]), "+v"(lo[7])
;                : "v"(a1) : "memory");
; #pragma unroll
; DI void mix_mem(CP& p, int l, int it, LAS unsigned char* lds) {
;     ...
;     sum += shx<16>(sum, lane); sum += shx<32>(sum, lane);
;     const float inv = 1.f / sum;
;     f32x4 o[8];
; #pragma unroll
;     for (int c = 0; c < 8; ++c) o[c] = (f32x4){0.f, 0.f, 0.f, 0.f};
; #pragma unroll
;     for (int s = 0; s < 8; ++s) {
;       u32x4 wp; wp.x = pk2(sc[2 * s].x * inv, sc[2 * s].y * inv); wp.y = pk2(sc[2 * s].z * inv, sc[2 * s].w * inv);
;       wp.z = pk2(sc[2 * s + 1].x * inv, sc[2 * s + 1].y * inv); wp.w = pk2(sc[2 * s + 1].z * inv, sc[2 * s + 1].w * inv);
;       const bf16x8 wf = __builtin_bit_cast(bf16x8, wp);
;       bf16x8 vf8[8]; gather_v8(vbuf, s, fr, fq, vf8);
; #pragma unroll
;       for (int c = 0; c < 8; ++c) o[c] = __builtin_amdgcn_mfma_f32_16x16x32_bf16(vf8[c], wf, o[c], 0, 0, 0);
	v_sub_f32_e32 v12, v61, v20
	v_mul_f32_e32 v12, 0x3fb8aa3b, v12
	v_exp_f32_e32 v105, v12
	v_sub_f32_e32 v12, v62, v20
	v_mul_f32_e32 v12, 0x3fb8aa3b, v12
	v_exp_f32_e32 v107, v12
	v_sub_f32_e32 v12, v63, v20
	v_mul_f32_e32 v12, 0x3fb8aa3b, v12
	v_exp_f32_e32 v109, v12
	v_sub_f32_e32 v12, v64, v20
	v_mul_f32_e32 v12, 0x3fb8aa3b, v12
	v_exp_f32_e32 v92, v12
	v_sub_f32_e32 v12, v65, v20
	v_mul_f32_e32 v12, 0x3fb8aa3b, v12
	v_exp_f32_e32 v90, v12
	v_sub_f32_e32 v12, v66, v20
	v_mul_f32_e32 v12, 0x3fb8aa3b, v12
	v_exp_f32_e32 v88, v12
	v_sub_f32_e32 v12, v67, v20
	v_mul_f32_e32 v12, 0x3fb8aa3b, v12
	v_exp_f32_e32 v86, v12
	v_add_f32_e32 v93, v103, v105
	v_add_f32_e32 v91, v107, v109
	v_pk_add_f32 v[12:13], v[92:93], v[90:91]
	v_pk_add_f32 v[14:15], v[88:89], v[86:87]
	s_nop 0
	v_pk_add_f32 v[12:13], v[12:13], v[14:15]
	s_nop 0
	v_pk_add_f32 v[84:85], v[12:13], v[12:13] op_sel_hi:[0,1]
	v_sub_f32_e32 v12, v68, v20
	v_mul_f32_e32 v12, 0x3fb8aa3b, v12
	v_exp_f32_e32 v94, v12
	v_sub_f32_e32 v12, v69, v20
	v_mul_f32_e32 v12, 0x3fb8aa3b, v12
	v_exp_f32_e32 v98, v12
	v_sub_f32_e32 v12, v70, v20
	v_mul_f32_e32 v12, 0x3fb8aa3b, v12
	v_exp_f32_e32 v95, v12
	v_sub_f32_e32 v12, v71, v20
	v_mul_f32_e32 v12, 0x3fb8aa3b, v12
	v_exp_f32_e32 v99, v12
	s_nop 0
	v_pk_add_f32 v[12:13], v[94:95], v[98:99]
	s_nop 0
	v_pk_add_f32 v[68:69], v[12:13], v[12:13] op_sel_hi:[0,1]
	v_sub_f32_e32 v12, v72, v20
	v_mul_f32_e32 v12, 0x3fb8aa3b, v12
	v_exp_f32_e32 v79, v12
	v_sub_f32_e32 v12, v73, v20
	v_mul_f32_e32 v12, 0x3fb8aa3b, v12
	v_exp_f32_e32 v72, v0
	v_sub_f32_e32 v0, v1, v20
	v_exp_f32_e32 v87, v12
	v_sub_f32_e32 v12, v74, v20
	v_mul_f32_e32 v0, 0x3fb8aa3b, v0
	v_mul_f32_e32 v12, 0x3fb8aa3b, v12
	v_exp_f32_e32 v70, v0
	v_sub_f32_e32 v0, v2, v20
	v_exp_f32_e32 v74, v12
	v_sub_f32_e32 v12, v75, v20
	v_mul_f32_e32 v0, 0x3fb8aa3b, v0
	v_mul_f32_e32 v12, 0x3fb8aa3b, v12
	v_exp_f32_e32 v68, v0
	v_sub_f32_e32 v0, v3, v20
	v_exp_f32_e32 v75, v12
	v_mul_f32_e32 v0, 0x3fb8aa3b, v0
	v_exp_f32_e32 v84, v0
	v_add_f32_e32 v73, v79, v87
	v_add_f32_e32 v71, v74, v75
	v_pk_add_f32 v[0:1], v[72:73], v[70:71]
	v_pk_add_f32 v[2:3], v[68:69], v[84:85]
	s_nop 0
	v_pk_add_f32 v[0:1], v[0:1], v[2:3]
	s_nop 0
	v_add_f32_e32 v0, v0, v1
	ds_swizzle_b32 v1, v0 offset:swizzle(SWAP,16)
	s_waitcnt lgkmcnt(0)
	v_add_f32_e32 v0, v0, v1
	ds_bpermute_b32 v1, v136, v0
	s_waitcnt lgkmcnt(0)
	v_add_f32_e32 v0, v0, v1
	v_div_scale_f32 v1, s[4:5], v0, v0, 1.0
	v_rcp_f32_e32 v2, v1
	s_mov_b64 s[4:5], 0x2c00
	v_fma_f32 v3, -v1, v2, 1.0
	v_fmac_f32_e32 v2, v3, v2
	v_div_scale_f32 v3, vcc, 1.0, v0, 1.0
	v_mul_f32_e32 v12, v3, v2
	v_fma_f32 v13, -v1, v12, v3
	v_fmac_f32_e32 v12, v13, v2
	v_fma_f32 v1, -v1, v12, v3
	v_div_fmas_f32 v1, v1, v2, v12
	v_div_fixup_f32 v69, v1, v0, 1.0
	v_mul_f32_e32 v0, v4, v69
	v_mul_f32_e32 v1, v6, v69
	v_cvt_pk_bf16_f32 v0, v0, v1
	v_mul_f32_e32 v1, v5, v69
	v_mul_f32_e32 v2, v7, v69
	v_cvt_pk_bf16_f32 v1, v1, v2
	v_mul_f32_e32 v2, v8, v69
	v_mul_f32_e32 v3, v10, v69
	v_cvt_pk_bf16_f32 v2, v2, v3
	v_mul_f32_e32 v3, v9, v69
	v_mul_f32_e32 v4, v11, v69
	v_cvt_pk_bf16_f32 v3, v3, v4
	ds_read_b64_tr_b16 v[4:5], v138
	ds_read_b64_tr_b16 v[8:9], v138 offset:32
	ds_read_b64_tr_b16 v[12:13], v138 offset:64
	ds_read_b64_tr_b16 v[16:17], v138 offset:96
	ds_read_b64_tr_b16 v[20:21], v138 offset:128
	ds_read_b64_tr_b16 v[24:25], v138 offset:160
	ds_read_b64_tr_b16 v[28:29], v138 offset:192
	ds_read_b64_tr_b16 v[32:33], v138 offset:224
	s_nop 0
	ds_read_b64_tr_b16 v[6:7], v139
	ds_read_b64_tr_b16 v[10:11], v139 offset:32
	ds_read_b64_tr_b16 v[14:15], v139 offset:64
	ds_read_b64_tr_b16 v[18:19], v139 offset:96
	ds_read_b64_tr_b16 v[22:23], v139 offset:128
	ds_read_b64_tr_b16 v[26:27], v139 offset:160
	ds_read_b64_tr_b16 v[30:31], v139 offset:192
	ds_read_b64_tr_b16 v[34:35], v139 offset:224
	s_waitcnt lgkmcnt(0)
	s_nop 0
	v_mfma_f32_16x16x32_bf16 v[4:7], v[4:7], v[0:3], 0
	v_mfma_f32_16x16x32_bf16 v[8:11], v[8:11], v[0:3], 0
	v_mfma_f32_16x16x32_bf16 v[12:15], v[12:15], v[0:3], 0
	v_mfma_f32_16x16x32_bf16 v[16:19], v[16:19], v[0:3], 0
	v_mfma_f32_16x16x32_bf16 v[20:23], v[20:23], v[0:3], 0
	v_mfma_f32_16x16x32_bf16 v[24:27], v[24:27], v[0:3], 0
	v_mfma_f32_16x16x32_bf16 v[28:31], v[28:31], v[0:3], 0
	v_mfma_f32_16x16x32_bf16 v[32:35], v[32:35], v[0:3], 0
	v_mul_f32_e32 v0, v158, v69
	v_mul_f32_e32 v1, v159, v69
	v_cvt_pk_bf16_f32 v36, v0, v1
	v_mul_f32_e32 v0, v160, v69
	v_mul_f32_e32 v1, v161, v69
	v_cvt_pk_bf16_f32 v37, v0, v1
	v_mul_f32_e32 v0, v132, v69
	v_mul_f32_e32 v1, v130, v69
	v_cvt_pk_bf16_f32 v38, v0, v1
	v_mul_f32_e32 v0, v128, v69
	v_mul_f32_e32 v1, v126, v69
	v_cvt_pk_bf16_f32 v39, v0, v1
	ds_read_b64_tr_b16 v[0:1], v140
	ds_read_b64_tr_b16 v[64:65], v140 offset:32
	ds_read_b64_tr_b16 v[60:61], v140 offset:64
	ds_read_b64_tr_b16 v[56:57], v140 offset:96
	ds_read_b64_tr_b16 v[52:53], v140 offset:128
	ds_read_b64_tr_b16 v[48:49], v140 offset:160
	ds_read_b64_tr_b16 v[44:45], v140 offset:192
	ds_read_b64_tr_b16 v[40:41], v140 offset:224
	s_nop 0
	ds_read_b64_tr_b16 v[2:3], v141
	ds_read_b64_tr_b16 v[42:43], v141 offset:32
	ds_read_b64_tr_b16 v[46:47], v141 offset:64
	ds_read_b64_tr_b16 v[50:51], v141 offset:96
	ds_read_b64_tr_b16 v[54:55], v141 offset:128
	ds_read_b64_tr_b16 v[158:159], v141 offset:160
	ds_read_b64_tr_b16 v[160:161], v141 offset:192
	ds_read_b64_tr_b16 v[162:163], v141 offset:224
	s_waitcnt lgkmcnt(0)
; #define LAS __attribute__((address_space(3)))
; DI unsigned pk2(float lo, float hi) { unsigned r; asm("v_cvt_pk_bf16_f32 %0, %1, %2" : "=v"(r) : "v"(lo), "v"(hi)); return r; }
; DI void gather_v8(const LAS u16* vb, int s, int fr, int fq, bf16x8* vf) {
;   const int q = fr >> 2, pp = fr & 3;
;   const unsigned a0 = (unsigned)(unsigned long)(vb + (32 * s + 4 * fq + q) * VSTR2) + 8u * pp;
;   const unsigned a1 = a0 + 16u * VSTR2 * 2u;
;   u32x2 lo[8], hi[8];
;   asm volatile("ds_read_b64_tr_b16 %0, %8\n\tds_read_b64_tr_b16 %1, %8 offset:32\n\tds_read_b64_tr_b16 %2, %8 offset:64\n\tds_read_b64_tr_b16 %3, %8 offset:96\n\t"
;                "ds_read_b64_tr_b16 %4, %8 offset:128\n\tds_read_b64_tr_b16 %5, %8 offset:160\n\tds_read_b64_tr_b16 %6, %8 offset:192\n\tds_read_b64_tr_b16 %7, %8 offset:224"
;                : "=&v"(lo[0]), "=&v"(lo[1]), "=&v"(lo[2]), "=&v"(lo[3]), "=&v"(lo[4]), "=&v"(lo[5]), "=&v"(lo[6]), "=&v"(lo[7]) : "v"(a0) : "memory");
;   asm volatile("ds_read_b64_tr_b16 %0, %16\n\tds_read_b64_tr_b16 %1, %16 offset:32\n\tds_read_b64_tr_b16 %2, %16 offset:64\n\tds_read_b64_tr_b16 %3, %16 offset:96\n\t"
;                "ds_read_b64_tr_b16 %4, %16 offset:128\n\tds_read_b64_tr_b16 %5, %16 offset:160\n\tds_read_b64_tr_b16 %6, %16 offset:192\n\tds_read_b64_tr_b16 %7, %16 offset:224\n\t"
;                "s_waitcnt lgkmcnt(0)"
;                : "=&v"(hi[0]), "=&v"(hi[1]), "=&v"(hi[2]), "=&v"(hi[3]), "=&v"(hi[4]), "=&v"(hi[5]), "=&v"(hi[6]), "=&v"(hi[7]),
;                  "+v"(lo[0]), "+v"(lo[1]), "+v"(lo[2]), "+v"(lo[3]), "+v"(lo[4]), "+v"(lo[5]), "+v"(lo[6]), "+v"(lo[7])
;                : "v"(a1) : "memory");
; #pragma unroll
;   for (int c = 0; c < 8; ++c) { const u32x4 t = {lo[c].x, lo[c].y, hi[c].x, hi[c].y}; vf[c] = __builtin_bit_cast(bf16x8, t); }
; }
; DI void mix_mem(CP& p, int l, int it, LAS unsigned char* lds) {
;     ...
; #pragma unroll
;     for (int s = 0; s < 8; ++s) {
;       u32x4 wp; wp.x = pk2(sc[2 * s].x * inv, sc[2 * s].y * inv); wp.y = pk2(sc[2 * s].z * inv, sc[2 * s].w * inv);
;       wp.z = pk2(sc[2 * s + 1].x * inv, sc[2 * s + 1].y * inv); wp.w = pk2(sc[2 * s + 1].z * inv, sc[2 * s + 1].w * inv);
;       const bf16x8 wf = __builtin_bit_cast(bf16x8, wp);
;       bf16x8 vf8[8]; gather_v8(vbuf, s, fr, fq, vf8);
; #pragma unroll
;       for (int c = 0; c < 8; ++c) o[c] = __builtin_amdgcn_mfma_f32_16x16x32_bf16(vf8[c], wf, o[c], 0, 0, 0);
	s_nop 0
	v_mov_b32_e32 v66, v42
	v_mov_b32_e32 v67, v43
	v_mov_b32_e32 v62, v46
	v_mov_b32_e32 v63, v47
	v_mov_b32_e32 v58, v50
	v_mov_b32_e32 v59, v51
	v_mov_b32_e32 v50, v158
	v_mov_b32_e32 v51, v159
	v_mov_b32_e32 v46, v160
	v_mov_b32_e32 v47, v161
	v_mov_b32_e32 v42, v162
	v_mov_b32_e32 v43, v163
	v_mfma_f32_16x16x32_bf16 v[0:3], v[0:3], v[36:39], v[4:7]
	v_mfma_f32_16x16x32_bf16 v[4:7], v[64:67], v[36:39], v[8:11]
	v_mfma_f32_16x16x32_bf16 v[8:11], v[60:63], v[36:39], v[12:15]
	v_mfma_f32_16x16x32_bf16 v[12:15], v[56:59], v[36:39], v[16:19]
	v_mfma_f32_16x16x32_bf16 v[16:19], v[52:55], v[36:39], v[20:23]
	v_mfma_f32_16x16x32_bf16 v[20:23], v[48:51], v[36:39], v[24:27]
	v_mfma_f32_16x16x32_bf16 v[24:27], v[44:47], v[36:39], v[28:31]
	v_mfma_f32_16x16x32_bf16 v[28:31], v[40:43], v[36:39], v[32:35]
	v_mul_f32_e32 v36, v133, v69
	s_nop 1
	v_mul_f32_e32 v32, v122, v69
	v_mul_f32_e32 v33, v124, v69
	v_cvt_pk_bf16_f32 v32, v32, v33
	v_mul_f32_e32 v33, v123, v69
	v_mul_f32_e32 v34, v125, v69
	v_cvt_pk_bf16_f32 v33, v33, v34
	v_mul_f32_e32 v34, v127, v69
	v_mul_f32_e32 v35, v129, v69
	v_cvt_pk_bf16_f32 v34, v34, v35
	v_mul_f32_e32 v35, v131, v69
	v_cvt_pk_bf16_f32 v35, v35, v36
	ds_read_b64_tr_b16 v[64:65], v142
	ds_read_b64_tr_b16 v[60:61], v142 offset:32
	ds_read_b64_tr_b16 v[56:57], v142 offset:64
	ds_read_b64_tr_b16 v[52:53], v142 offset:96
	ds_read_b64_tr_b16 v[48:49], v142 offset:128
	ds_read_b64_tr_b16 v[44:45], v142 offset:160
	ds_read_b64_tr_b16 v[40:41], v142 offset:192
	ds_read_b64_tr_b16 v[36:37], v142 offset:224
	s_nop 0
	ds_read_b64_tr_b16 v[38:39], v143
	ds_read_b64_tr_b16 v[42:43], v143 offset:32
	ds_read_b64_tr_b16 v[46:47], v143 offset:64
	ds_read_b64_tr_b16 v[50:51], v143 offset:96
	ds_read_b64_tr_b16 v[122:123], v143 offset:128
	ds_read_b64_tr_b16 v[124:125], v143 offset:160
	ds_read_b64_tr_b16 v[126:127], v143 offset:192
	ds_read_b64_tr_b16 v[128:129], v143 offset:224
	s_waitcnt lgkmcnt(0)
	s_nop 0
	v_mov_b32_e32 v66, v38
	v_mov_b32_e32 v67, v39
	v_mov_b32_e32 v62, v42
	v_mov_b32_e32 v63, v43
	v_mov_b32_e32 v58, v46
	v_mov_b32_e32 v59, v47
	v_mov_b32_e32 v54, v50
	v_mov_b32_e32 v55, v51
	v_mov_b32_e32 v50, v122
	v_mov_b32_e32 v51, v123
	v_mov_b32_e32 v46, v124
	v_mov_b32_e32 v47, v125
	v_mov_b32_e32 v42, v126
	v_mov_b32_e32 v43, v127
	v_mov_b32_e32 v38, v128
	v_mov_b32_e32 v39, v129
	v_mfma_f32_16x16x32_bf16 v[0:3], v[64:67], v[32:35], v[0:3]
	v_mfma_f32_16x16x32_bf16 v[4:7], v[60:63], v[32:35], v[4:7]
	v_mfma_f32_16x16x32_bf16 v[8:11], v[56:59], v[32:35], v[8:11]
	v_mfma_f32_16x16x32_bf16 v[12:15], v[52:55], v[32:35], v[12:15]
	v_mfma_f32_16x16x32_bf16 v[16:19], v[48:51], v[32:35], v[16:19]
	v_mfma_f32_16x16x32_bf16 v[20:23], v[44:47], v[32:35], v[20:23]
	v_mfma_f32_16x16x32_bf16 v[24:27], v[40:43], v[32:35], v[24:27]
	v_mfma_f32_16x16x32_bf16 v[28:31], v[36:39], v[32:35], v[28:31]
	v_mul_f32_e32 v32, v116, v69
	v_mul_f32_e32 v33, v114, v69
	v_cvt_pk_bf16_f32 v32, v32, v33
	v_mul_f32_e32 v33, v112, v69
	v_mul_f32_e32 v34, v110, v69
	v_cvt_pk_bf16_f32 v33, v33, v34
	v_mul_f32_e32 v34, v118, v69
	v_mul_f32_e32 v35, v120, v69
	v_cvt_pk_bf16_f32 v34, v34, v35
	v_mul_f32_e32 v35, v119, v69
	v_mul_f32_e32 v36, v121, v69
	v_cvt_pk_bf16_f32 v35, v35, v36
	ds_read_b64_tr_b16 v[64:65], v148
	ds_read_b64_tr_b16 v[60:61], v148 offset:32
	ds_read_b64_tr_b16 v[56:57], v148 offset:64
	ds_read_b64_tr_b16 v[52:53], v148 offset:96
	ds_read_b64_tr_b16 v[48:49], v148 offset:128
	ds_read_b64_tr_b16 v[44:45], v148 offset:160
	ds_read_b64_tr_b16 v[40:41], v148 offset:192
	ds_read_b64_tr_b16 v[36:37], v148 offset:224
	s_nop 0
	ds_read_b64_tr_b16 v[38:39], v149
	ds_read_b64_tr_b16 v[42:43], v149 offset:32
	ds_read_b64_tr_b16 v[46:47], v149 offset:64
	ds_read_b64_tr_b16 v[50:51], v149 offset:96
	ds_read_b64_tr_b16 v[118:119], v149 offset:128
	ds_read_b64_tr_b16 v[120:121], v149 offset:160
	ds_read_b64_tr_b16 v[122:123], v149 offset:192
	ds_read_b64_tr_b16 v[124:125], v149 offset:224
	s_waitcnt lgkmcnt(0)
	s_nop 0
	v_mov_b32_e32 v66, v38
	v_mov_b32_e32 v67, v39
	v_mov_b32_e32 v62, v42
	v_mov_b32_e32 v63, v43
	v_mov_b32_e32 v58, v46
	v_mov_b32_e32 v59, v47
	v_mov_b32_e32 v54, v50
	v_mov_b32_e32 v55, v51
	v_mov_b32_e32 v50, v118
	v_mov_b32_e32 v51, v119
	v_mov_b32_e32 v46, v120
	v_mov_b32_e32 v47, v121
	v_mov_b32_e32 v42, v122
	v_mov_b32_e32 v43, v123
	v_mov_b32_e32 v38, v124
	v_mov_b32_e32 v39, v125
	v_mfma_f32_16x16x32_bf16 v[0:3], v[64:67], v[32:35], v[0:3]
	v_mfma_f32_16x16x32_bf16 v[4:7], v[60:63], v[32:35], v[4:7]
	v_mfma_f32_16x16x32_bf16 v[8:11], v[56:59], v[32:35], v[8:11]
	v_mfma_f32_16x16x32_bf16 v[12:15], v[52:55], v[32:35], v[12:15]
	v_mfma_f32_16x16x32_bf16 v[16:19], v[48:51], v[32:35], v[16:19]
	v_mfma_f32_16x16x32_bf16 v[20:23], v[44:47], v[32:35], v[20:23]
	v_mfma_f32_16x16x32_bf16 v[24:27], v[40:43], v[32:35], v[24:27]
	v_mfma_f32_16x16x32_bf16 v[28:31], v[36:39], v[32:35], v[28:31]
	v_mul_f32_e32 v32, v111, v69
	v_mul_f32_e32 v33, v113, v69
	v_cvt_pk_bf16_f32 v32, v32, v33
	v_mul_f32_e32 v33, v115, v69
	v_mul_f32_e32 v34, v117, v69
	v_cvt_pk_bf16_f32 v33, v33, v34
	v_mul_f32_e32 v34, v108, v69
	v_mul_f32_e32 v35, v106, v69
	v_cvt_pk_bf16_f32 v34, v34, v35
	v_mul_f32_e32 v35, v104, v69
	v_mul_f32_e32 v36, v102, v69
	v_cvt_pk_bf16_f32 v35, v35, v36
	ds_read_b64_tr_b16 v[64:65], v150
	ds_read_b64_tr_b16 v[60:61], v150 offset:32
	ds_read_b64_tr_b16 v[56:57], v150 offset:64
	ds_read_b64_tr_b16 v[52:53], v150 offset:96
	ds_read_b64_tr_b16 v[48:49], v150 offset:128
	ds_read_b64_tr_b16 v[44:45], v150 offset:160
	ds_read_b64_tr_b16 v[40:41], v150 offset:192
	ds_read_b64_tr_b16 v[36:37], v150 offset:224
	s_nop 0
	ds_read_b64_tr_b16 v[38:39], v151
	ds_read_b64_tr_b16 v[42:43], v151 offset:32
	ds_read_b64_tr_b16 v[46:47], v151 offset:64
	ds_read_b64_tr_b16 v[50:51], v151 offset:96
	ds_read_b64_tr_b16 v[110:111], v151 offset:128
	ds_read_b64_tr_b16 v[112:113], v151 offset:160
	ds_read_b64_tr_b16 v[114:115], v151 offset:192
	ds_read_b64_tr_b16 v[116:117], v151 offset:224
	s_waitcnt lgkmcnt(0)
; #define LAS __attribute__((address_space(3)))
; DI unsigned pk2(float lo, float hi) { unsigned r; asm("v_cvt_pk_bf16_f32 %0, %1, %2" : "=v"(r) : "v"(lo), "v"(hi)); return r; }
; DI void gather_v8(const LAS u16* vb, int s, int fr, int fq, bf16x8* vf) {
;   const int q = fr >> 2, pp = fr & 3;
;   const unsigned a0 = (unsigned)(unsigned long)(vb + (32 * s + 4 * fq + q) * VSTR2) + 8u * pp;
;   const unsigned a1 = a0 + 16u * VSTR2 * 2u;
;   u32x2 lo[8], hi[8];
;   asm volatile("ds_read_b64_tr_b16 %0, %8\n\tds_read_b64_tr_b16 %1, %8 offset:32\n\tds_read_b64_tr_b16 %2, %8 offset:64\n\tds_read_b64_tr_b16 %3, %8 offset:96\n\t"
;                "ds_read_b64_tr_b16 %4, %8 offset:128\n\tds_read_b64_tr_b16 %5, %8 offset:160\n\tds_read_b64_tr_b16 %6, %8 offset:192\n\tds_read_b64_tr_b16 %7, %8 offset:224"
;                : "=&v"(lo[0]), "=&v"(lo[1]), "=&v"(lo[2]), "=&v"(lo[3]), "=&v"(lo[4]), "=&v"(lo[5]), "=&v"(lo[6]), "=&v"(lo[7]) : "v"(a0) : "memory");
;   asm volatile("ds_read_b64_tr_b16 %0, %16\n\tds_read_b64_tr_b16 %1, %16 offset:32\n\tds_read_b64_tr_b16 %2, %16 offset:64\n\tds_read_b64_tr_b16 %3, %16 offset:96\n\t"
;                "ds_read_b64_tr_b16 %4, %16 offset:128\n\tds_read_b64_tr_b16 %5, %16 offset:160\n\tds_read_b64_tr_b16 %6, %16 offset:192\n\tds_read_b64_tr_b16 %7, %16 offset:224\n\t"
;                "s_waitcnt lgkmcnt(0)"
;                : "=&v"(hi[0]), "=&v"(hi[1]), "=&v"(hi[2]), "=&v"(hi[3]), "=&v"(hi[4]), "=&v"(hi[5]), "=&v"(hi[6]), "=&v"(hi[7]),
;                  "+v"(lo[0]), "+v"(lo[1]), "+v"(lo[2]), "+v"(lo[3]), "+v"(lo[4]), "+v"(lo[5]), "+v"(lo[6]), "+v"(lo[7])
;                : "v"(a1) : "memory");
; #pragma unroll
;   for (int c = 0; c < 8; ++c) { const u32x4 t = {lo[c].x, lo[c].y, hi[c].x, hi[c].y}; vf[c] = __builtin_bit_cast(bf16x8, t); }
; }
; DI void mix_mem(CP& p, int l, int it, LAS unsigned char* lds) {
;     ...
; #pragma unroll
;     for (int s = 0; s < 8; ++s) {
;       u32x4 wp; wp.x = pk2(sc[2 * s].x * inv, sc[2 * s].y * inv); wp.y = pk2(sc[2 * s].z * inv, sc[2 * s].w * inv);
;       wp.z = pk2(sc[2 * s + 1].x * inv, sc[2 * s + 1].y * inv); wp.w = pk2(sc[2 * s + 1].z * inv, sc[2 * s + 1].w * inv);
;       const bf16x8 wf = __builtin_bit_cast(bf16x8, wp);
;       bf16x8 vf8[8]; gather_v8(vbuf, s, fr, fq, vf8);
; #pragma unroll
;       for (int c = 0; c < 8; ++c) o[c] = __builtin_amdgcn_mfma_f32_16x16x32_bf16(vf8[c], wf, o[c], 0, 0, 0);
	s_nop 0
	v_mov_b32_e32 v66, v38
	v_mov_b32_e32 v67, v39
	v_mov_b32_e32 v62, v42
	v_mov_b32_e32 v63, v43
	v_mov_b32_e32 v58, v46
	v_mov_b32_e32 v59, v47
	v_mov_b32_e32 v54, v50
	v_mov_b32_e32 v55, v51
	v_mov_b32_e32 v50, v110
	v_mov_b32_e32 v51, v111
	v_mov_b32_e32 v46, v112
	v_mov_b32_e32 v47, v113
	v_mov_b32_e32 v42, v114
	v_mov_b32_e32 v43, v115
	v_mov_b32_e32 v38, v116
	v_mov_b32_e32 v39, v117
	v_mfma_f32_16x16x32_bf16 v[0:3], v[64:67], v[32:35], v[0:3]
	v_mfma_f32_16x16x32_bf16 v[4:7], v[60:63], v[32:35], v[4:7]
	v_mfma_f32_16x16x32_bf16 v[8:11], v[56:59], v[32:35], v[8:11]
	v_mfma_f32_16x16x32_bf16 v[12:15], v[52:55], v[32:35], v[12:15]
	v_mfma_f32_16x16x32_bf16 v[16:19], v[48:51], v[32:35], v[16:19]
	v_mfma_f32_16x16x32_bf16 v[20:23], v[44:47], v[32:35], v[20:23]
	v_mfma_f32_16x16x32_bf16 v[24:27], v[40:43], v[32:35], v[24:27]
	v_mfma_f32_16x16x32_bf16 v[28:31], v[36:39], v[32:35], v[28:31]
	v_mul_f32_e32 v32, v96, v69
	v_mul_f32_e32 v33, v100, v69
	v_cvt_pk_bf16_f32 v32, v32, v33
	v_mul_f32_e32 v33, v97, v69
	v_mul_f32_e32 v34, v101, v69
	v_cvt_pk_bf16_f32 v33, v33, v34
	v_mul_f32_e32 v34, v103, v69
	v_mul_f32_e32 v35, v105, v69
	v_cvt_pk_bf16_f32 v34, v34, v35
	v_mul_f32_e32 v35, v107, v69
	v_mul_f32_e32 v36, v109, v69
	v_cvt_pk_bf16_f32 v35, v35, v36
	ds_read_b64_tr_b16 v[64:65], v152
	ds_read_b64_tr_b16 v[60:61], v152 offset:32
	ds_read_b64_tr_b16 v[56:57], v152 offset:64
	ds_read_b64_tr_b16 v[52:53], v152 offset:96
	ds_read_b64_tr_b16 v[48:49], v152 offset:128
	ds_read_b64_tr_b16 v[44:45], v152 offset:160
	ds_read_b64_tr_b16 v[40:41], v152 offset:192
	ds_read_b64_tr_b16 v[36:37], v152 offset:224
	s_nop 0
	ds_read_b64_tr_b16 v[38:39], v153
	ds_read_b64_tr_b16 v[42:43], v153 offset:32
	ds_read_b64_tr_b16 v[46:47], v153 offset:64
	ds_read_b64_tr_b16 v[50:51], v153 offset:96
	ds_read_b64_tr_b16 v[96:97], v153 offset:128
	ds_read_b64_tr_b16 v[100:101], v153 offset:160
	ds_read_b64_tr_b16 v[102:103], v153 offset:192
	ds_read_b64_tr_b16 v[104:105], v153 offset:224
	s_waitcnt lgkmcnt(0)
	s_nop 0
	v_mov_b32_e32 v66, v38
	v_mov_b32_e32 v67, v39
	v_mov_b32_e32 v62, v42
	v_mov_b32_e32 v63, v43
	v_mov_b32_e32 v58, v46
	v_mov_b32_e32 v59, v47
	v_mov_b32_e32 v54, v50
	v_mov_b32_e32 v55, v51
	v_mov_b32_e32 v50, v96
	v_mov_b32_e32 v51, v97
	v_mov_b32_e32 v46, v100
	v_mov_b32_e32 v47, v101
	v_mov_b32_e32 v42, v102
	v_mov_b32_e32 v43, v103
	v_mov_b32_e32 v38, v104
	v_mov_b32_e32 v39, v105
	v_mfma_f32_16x16x32_bf16 v[0:3], v[64:67], v[32:35], v[0:3]
	v_mfma_f32_16x16x32_bf16 v[4:7], v[60:63], v[32:35], v[4:7]
	v_mfma_f32_16x16x32_bf16 v[8:11], v[56:59], v[32:35], v[8:11]
	v_mfma_f32_16x16x32_bf16 v[12:15], v[52:55], v[32:35], v[12:15]
	v_mfma_f32_16x16x32_bf16 v[16:19], v[48:51], v[32:35], v[16:19]
	v_mfma_f32_16x16x32_bf16 v[20:23], v[44:47], v[32:35], v[20:23]
	v_mfma_f32_16x16x32_bf16 v[24:27], v[40:43], v[32:35], v[24:27]
	v_mfma_f32_16x16x32_bf16 v[28:31], v[36:39], v[32:35], v[28:31]
	v_mul_f32_e32 v32, v92, v69
	v_mul_f32_e32 v33, v90, v69
	v_cvt_pk_bf16_f32 v32, v32, v33
	v_mul_f32_e32 v33, v88, v69
	v_mul_f32_e32 v34, v86, v69
	v_cvt_pk_bf16_f32 v33, v33, v34
	v_mul_f32_e32 v34, v94, v69
	v_mul_f32_e32 v35, v98, v69
	v_cvt_pk_bf16_f32 v34, v34, v35
	v_mul_f32_e32 v35, v95, v69
	v_mul_f32_e32 v36, v99, v69
	v_cvt_pk_bf16_f32 v35, v35, v36
	ds_read_b64_tr_b16 v[64:65], v154
	ds_read_b64_tr_b16 v[60:61], v154 offset:32
	ds_read_b64_tr_b16 v[56:57], v154 offset:64
	ds_read_b64_tr_b16 v[52:53], v154 offset:96
	ds_read_b64_tr_b16 v[48:49], v154 offset:128
	ds_read_b64_tr_b16 v[44:45], v154 offset:160
	ds_read_b64_tr_b16 v[40:41], v154 offset:192
	ds_read_b64_tr_b16 v[36:37], v154 offset:224
	s_nop 0
	ds_read_b64_tr_b16 v[38:39], v155
	ds_read_b64_tr_b16 v[42:43], v155 offset:32
	ds_read_b64_tr_b16 v[46:47], v155 offset:64
	ds_read_b64_tr_b16 v[50:51], v155 offset:96
	ds_read_b64_tr_b16 v[88:89], v155 offset:128
	ds_read_b64_tr_b16 v[90:91], v155 offset:160
	ds_read_b64_tr_b16 v[92:93], v155 offset:192
	ds_read_b64_tr_b16 v[94:95], v155 offset:224
	s_waitcnt lgkmcnt(0)
	s_nop 0
	v_mov_b32_e32 v54, v50
	v_mov_b32_e32 v55, v51
	v_mov_b32_e32 v50, v88
	v_mov_b32_e32 v51, v89
	v_mov_b32_e32 v66, v38
	v_mov_b32_e32 v67, v39
	v_mov_b32_e32 v62, v42
	v_mov_b32_e32 v63, v43
	v_mov_b32_e32 v58, v46
	v_mov_b32_e32 v59, v47
	v_mov_b32_e32 v46, v90
	v_mov_b32_e32 v47, v91
	v_mov_b32_e32 v42, v92
	v_mov_b32_e32 v43, v93
	v_mov_b32_e32 v38, v94
	v_mov_b32_e32 v39, v95
	v_mfma_f32_16x16x32_bf16 v[48:51], v[48:51], v[32:35], v[16:19]
	s_nop 2
	v_mul_f32_e32 v16, v79, v69
	v_mul_f32_e32 v17, v87, v69
	v_mfma_f32_16x16x32_bf16 v[0:3], v[64:67], v[32:35], v[0:3]
	v_mov_b32_e32 v79, v147
	v_mfma_f32_16x16x32_bf16 v[4:7], v[60:63], v[32:35], v[4:7]
	v_mfma_f32_16x16x32_bf16 v[8:11], v[56:59], v[32:35], v[8:11]
	v_mfma_f32_16x16x32_bf16 v[12:15], v[52:55], v[32:35], v[12:15]
	v_mfma_f32_16x16x32_bf16 v[44:47], v[44:47], v[32:35], v[20:23]
	v_mfma_f32_16x16x32_bf16 v[40:43], v[40:43], v[32:35], v[24:27]
	v_mfma_f32_16x16x32_bf16 v[32:35], v[36:39], v[32:35], v[28:31]
	v_cvt_pk_bf16_f32 v36, v16, v17
	v_mul_f32_e32 v16, v74, v69
	v_mul_f32_e32 v17, v75, v69
	v_cvt_pk_bf16_f32 v37, v16, v17
	v_mul_f32_e32 v16, v72, v69
	v_mul_f32_e32 v17, v70, v69
	v_cvt_pk_bf16_f32 v38, v16, v17
	v_mul_f32_e32 v16, v68, v69
	v_mul_f32_e32 v17, v84, v69
	v_cvt_pk_bf16_f32 v39, v16, v17
	ds_read_b64_tr_b16 v[28:29], v156
	ds_read_b64_tr_b16 v[24:25], v156 offset:32
	ds_read_b64_tr_b16 v[20:21], v156 offset:64
	ds_read_b64_tr_b16 v[16:17], v156 offset:96
	ds_read_b64_tr_b16 v[64:65], v156 offset:128
	ds_read_b64_tr_b16 v[60:61], v156 offset:160
	ds_read_b64_tr_b16 v[56:57], v156 offset:192
	ds_read_b64_tr_b16 v[52:53], v156 offset:224
	s_nop 0
	ds_read_b64_tr_b16 v[18:19], v157
	ds_read_b64_tr_b16 v[22:23], v157 offset:32
	ds_read_b64_tr_b16 v[54:55], v157 offset:64
	ds_read_b64_tr_b16 v[58:59], v157 offset:96
	ds_read_b64_tr_b16 v[62:63], v157 offset:128
	ds_read_b64_tr_b16 v[68:69], v157 offset:160
	ds_read_b64_tr_b16 v[70:71], v157 offset:192
	ds_read_b64_tr_b16 v[72:73], v157 offset:224
	s_waitcnt lgkmcnt(0)
; DI unsigned pk2(float lo, float hi) { unsigned r; asm("v_cvt_pk_bf16_f32 %0, %1, %2" : "=v"(r) : "v"(lo), "v"(hi)); return r; }
; DI float bflo(unsigned u) { return __uint_as_float(u << 16); }
; DI float bfhi(unsigned u) { return __uint_as_float(u & 0xffff0000u); }
; DI float silu(float x) { return x * __builtin_amdgcn_rcpf(1.f + __expf(-x)); }
; DI void mix_mem(CP& p, int l, int it, LAS unsigned char* lds) {
;     ...
;       for (int c = 0; c < 8; ++c) o[c] = __builtin_amdgcn_mfma_f32_16x16x32_bf16(vf8[c], wf, o[c], 0, 0, 0);
;     }
;     const u16* mg = proj + (size_t)rowq * NPROJ + C_MG + hh * 128;
;     u16* yo = y + (size_t)rowq * DM + 1536 + hh * 128;
; #pragma unroll
;     for (int c = 0; c < 8; ++c) {
;       const int d0 = 16 * c + 4 * fq;
;       const u32x2 g = *(const u32x2*)(mg + d0);
;       u32x2 ov; ov.x = pk2(o[c].x * silu(bflo(g.x)), o[c].y * silu(bfhi(g.x))); ov.y = pk2(o[c].z * silu(bflo(g.y)), o[c].w * silu(bfhi(g.y)));
;       *(u32x2*)(yo + d0) = ov;
;     }
	s_nop 0
	v_mov_b32_e32 v30, v18
	v_mov_b32_e32 v31, v19
	v_mov_b32_e32 v26, v22
	v_mov_b32_e32 v27, v23
	v_mov_b32_e32 v22, v54
	v_mov_b32_e32 v23, v55
	v_mov_b32_e32 v54, v72
	v_mov_b32_e32 v55, v73
	v_mov_b32_e32 v18, v58
	v_mov_b32_e32 v19, v59
	v_mov_b32_e32 v66, v62
	v_mov_b32_e32 v67, v63
	v_mov_b32_e32 v62, v68
	v_mov_b32_e32 v63, v69
	v_mov_b32_e32 v58, v70
	v_mov_b32_e32 v59, v71
	v_mfma_f32_16x16x32_bf16 v[28:31], v[28:31], v[36:39], v[0:3]
	v_mfma_f32_16x16x32_bf16 v[0:3], v[52:55], v[36:39], v[32:35]
	s_nop 2
	v_lshlrev_b64 v[32:33], 12, v[82:83]
	v_mfma_f32_16x16x32_bf16 v[24:27], v[24:27], v[36:39], v[4:7]
	v_lshl_add_u64 v[32:33], s[12:13], 0, v[32:33]
	v_lshl_add_u64 v[34:35], v[32:33], 0, s[38:39]
	v_mfma_f32_16x16x32_bf16 v[20:23], v[20:23], v[36:39], v[8:11]
	v_mfma_f32_16x16x32_bf16 v[16:19], v[16:19], v[36:39], v[12:15]
	v_mfma_f32_16x16x32_bf16 v[12:15], v[64:67], v[36:39], v[48:51]
	v_mfma_f32_16x16x32_bf16 v[8:11], v[60:63], v[36:39], v[44:47]
	v_mfma_f32_16x16x32_bf16 v[4:7], v[56:59], v[36:39], v[40:43]
	v_lshl_add_u64 v[36:37], v[80:81], 0, v[78:79]
	v_lshl_add_u64 v[32:33], v[36:37], 0, s[4:5]
	v_add_co_u32_e32 v36, vcc, s82, v36
	s_mov_b64 s[4:5], 0xdd40c00
	s_nop 0
	v_addc_co_u32_e32 v37, vcc, 0, v37, vcc
	s_nop 1
	v_mov_b32_e32 v36, v172
	v_mov_b32_e32 v37, v173
	v_lshlrev_b32_e32 v38, 16, v36
	v_mul_f32_e32 v39, 0xbfb8aa3b, v38
	v_exp_f32_e32 v39, v39
	v_and_b32_e32 v36, 0xffff0000, v36
	v_add_f32_e32 v39, 1.0, v39
	v_rcp_f32_e32 v39, v39
	s_nop 0
	v_mul_f32_e32 v38, v39, v38
	v_mul_f32_e32 v28, v28, v38
	v_mul_f32_e32 v38, 0xbfb8aa3b, v36
	v_exp_f32_e32 v38, v38
	s_nop 0
	v_add_f32_e32 v38, 1.0, v38
	v_rcp_f32_e32 v38, v38
	s_nop 0
	v_mul_f32_e32 v36, v38, v36
	v_mul_f32_e32 v29, v29, v36
	v_cvt_pk_bf16_f32 v36, v28, v29
	v_lshlrev_b32_e32 v28, 16, v37
	v_mul_f32_e32 v29, 0xbfb8aa3b, v28
	v_exp_f32_e32 v29, v29
	s_nop 0
	v_add_f32_e32 v29, 1.0, v29
	v_rcp_f32_e32 v29, v29
	s_nop 0
	v_mul_f32_e32 v28, v29, v28
	v_and_b32_e32 v29, 0xffff0000, v37
	v_mul_f32_e32 v28, v30, v28
	v_mul_f32_e32 v30, 0xbfb8aa3b, v29
	v_exp_f32_e32 v30, v30
	s_nop 0
	v_add_f32_e32 v30, 1.0, v30
	v_rcp_f32_e32 v30, v30
	s_nop 0
	v_mul_f32_e32 v29, v30, v29
	v_mul_f32_e32 v29, v31, v29
	v_lshl_add_u64 v[30:31], v[34:35], 0, v[78:79]
	v_cvt_pk_bf16_f32 v37, v28, v29
	v_lshl_add_u64 v[28:29], v[30:31], 0, s[4:5]
	v_add_co_u32_e32 v30, vcc, s98, v30
	s_movk_i32 s4, 0x80
	s_nop 0
	v_addc_co_u32_e32 v31, vcc, 0, v31, vcc
	global_store_dwordx2 v[30:31], v[36:37], off offset:3072
	s_nop 1
	v_mov_b32_e32 v30, v174
	v_mov_b32_e32 v31, v175
	s_and_b64 vcc, exec, s[6:7]
	v_lshlrev_b32_e32 v34, 16, v30
	v_mul_f32_e32 v35, 0xbfb8aa3b, v34
	v_exp_f32_e32 v35, v35
	v_and_b32_e32 v30, 0xffff0000, v30
	v_add_f32_e32 v35, 1.0, v35
	v_rcp_f32_e32 v35, v35
	s_nop 0
	v_mul_f32_e32 v34, v35, v34
	v_mul_f32_e32 v24, v24, v34
	v_mul_f32_e32 v34, 0xbfb8aa3b, v30
	v_exp_f32_e32 v34, v34
	s_nop 0
	v_add_f32_e32 v34, 1.0, v34
	v_rcp_f32_e32 v34, v34
	s_nop 0
	v_mul_f32_e32 v30, v34, v30
	v_mul_f32_e32 v25, v25, v30
	v_cvt_pk_bf16_f32 v24, v24, v25
	v_lshlrev_b32_e32 v25, 16, v31
	v_mul_f32_e32 v30, 0xbfb8aa3b, v25
	v_exp_f32_e32 v30, v30
	s_nop 0
	v_add_f32_e32 v30, 1.0, v30
	v_rcp_f32_e32 v30, v30
	s_nop 0
	v_mul_f32_e32 v25, v30, v25
	v_mul_f32_e32 v25, v26, v25
	v_and_b32_e32 v26, 0xffff0000, v31
	v_mul_f32_e32 v30, 0xbfb8aa3b, v26
	v_exp_f32_e32 v30, v30
	s_nop 0
	v_add_f32_e32 v30, 1.0, v30
	v_rcp_f32_e32 v30, v30
	s_nop 0
	v_mul_f32_e32 v26, v30, v26
	v_mul_f32_e32 v26, v27, v26
	v_cvt_pk_bf16_f32 v25, v25, v26
	global_store_dwordx2 v[28:29], v[24:25], off offset:32
	s_nop 1
	v_mov_b32_e32 v24, v176
	v_mov_b32_e32 v25, v177
	v_lshlrev_b32_e32 v26, 16, v24
	v_mul_f32_e32 v27, 0xbfb8aa3b, v26
	v_exp_f32_e32 v27, v27
	v_and_b32_e32 v24, 0xffff0000, v24
	v_add_f32_e32 v27, 1.0, v27
	v_rcp_f32_e32 v27, v27
	s_nop 0
	v_mul_f32_e32 v26, v27, v26
	v_mul_f32_e32 v20, v20, v26
	v_mul_f32_e32 v26, 0xbfb8aa3b, v24
	v_exp_f32_e32 v26, v26
	s_nop 0
	v_add_f32_e32 v26, 1.0, v26
	v_rcp_f32_e32 v26, v26
	s_nop 0
	v_mul_f32_e32 v24, v26, v24
	v_mul_f32_e32 v21, v21, v24
	v_cvt_pk_bf16_f32 v20, v20, v21
	v_lshlrev_b32_e32 v21, 16, v25
	v_mul_f32_e32 v24, 0xbfb8aa3b, v21
	v_exp_f32_e32 v24, v24
	s_nop 0
	v_add_f32_e32 v24, 1.0, v24
	v_rcp_f32_e32 v24, v24
	s_nop 0
	v_mul_f32_e32 v21, v24, v21
	v_mul_f32_e32 v21, v22, v21
	v_and_b32_e32 v22, 0xffff0000, v25
	v_mul_f32_e32 v24, 0xbfb8aa3b, v22
	v_exp_f32_e32 v24, v24
	s_nop 0
	v_add_f32_e32 v24, 1.0, v24
	v_rcp_f32_e32 v24, v24
	s_nop 0
	v_mul_f32_e32 v22, v24, v22
	v_mul_f32_e32 v22, v23, v22
	v_cvt_pk_bf16_f32 v21, v21, v22
	global_store_dwordx2 v[28:29], v[20:21], off offset:64
	s_nop 1
	v_mov_b32_e32 v20, v178
	v_mov_b32_e32 v21, v179
	v_lshlrev_b32_e32 v22, 16, v20
	v_mul_f32_e32 v23, 0xbfb8aa3b, v22
	v_exp_f32_e32 v23, v23
	v_and_b32_e32 v20, 0xffff0000, v20
	v_add_f32_e32 v23, 1.0, v23
	v_rcp_f32_e32 v23, v23
	s_nop 0
	v_mul_f32_e32 v22, v23, v22
; DI unsigned pk2(float lo, float hi) { unsigned r; asm("v_cvt_pk_bf16_f32 %0, %1, %2" : "=v"(r) : "v"(lo), "v"(hi)); return r; }
; DI float bflo(unsigned u) { return __uint_as_float(u << 16); }
; DI float bfhi(unsigned u) { return __uint_as_float(u & 0xffff0000u); }
; DI float silu(float x) { return x * __builtin_amdgcn_rcpf(1.f + __expf(-x)); }
; DI void mix_mem(CP& p, int l, int it, LAS unsigned char* lds) {
;     ...
; #pragma unroll
;     for (int c = 0; c < 8; ++c) {
;       const int d0 = 16 * c + 4 * fq;
;       const u32x2 g = *(const u32x2*)(mg + d0);
;       u32x2 ov; ov.x = pk2(o[c].x * silu(bflo(g.x)), o[c].y * silu(bfhi(g.x))); ov.y = pk2(o[c].z * silu(bflo(g.y)), o[c].w * silu(bfhi(g.y)));
;       *(u32x2*)(yo + d0) = ov;
;     }
	v_mul_f32_e32 v16, v16, v22
	v_mul_f32_e32 v22, 0xbfb8aa3b, v20
	v_exp_f32_e32 v22, v22
	s_nop 0
	v_add_f32_e32 v22, 1.0, v22
	v_rcp_f32_e32 v22, v22
	s_nop 0
	v_mul_f32_e32 v20, v22, v20
	v_mul_f32_e32 v17, v17, v20
	v_cvt_pk_bf16_f32 v16, v16, v17
	v_lshlrev_b32_e32 v17, 16, v21
	v_mul_f32_e32 v20, 0xbfb8aa3b, v17
	v_exp_f32_e32 v20, v20
	s_nop 0
	v_add_f32_e32 v20, 1.0, v20
	v_rcp_f32_e32 v20, v20
	s_nop 0
	v_mul_f32_e32 v17, v20, v17
	v_mul_f32_e32 v17, v18, v17
	v_and_b32_e32 v18, 0xffff0000, v21
	v_mul_f32_e32 v20, 0xbfb8aa3b, v18
	v_exp_f32_e32 v20, v20
	s_nop 0
	v_add_f32_e32 v20, 1.0, v20
	v_rcp_f32_e32 v20, v20
	s_nop 0
	v_mul_f32_e32 v18, v20, v18
	v_mul_f32_e32 v18, v19, v18
	v_cvt_pk_bf16_f32 v17, v17, v18
	global_store_dwordx2 v[28:29], v[16:17], off offset:96
	s_nop 1
	v_mov_b32_e32 v16, v180
	v_mov_b32_e32 v17, v181
	v_lshlrev_b32_e32 v18, 16, v16
	v_mul_f32_e32 v19, 0xbfb8aa3b, v18
	v_exp_f32_e32 v19, v19
	v_and_b32_e32 v16, 0xffff0000, v16
	v_add_f32_e32 v19, 1.0, v19
	v_rcp_f32_e32 v19, v19
	s_nop 0
	v_mul_f32_e32 v18, v19, v18
	v_mul_f32_e32 v12, v12, v18
	v_mul_f32_e32 v18, 0xbfb8aa3b, v16
	v_exp_f32_e32 v18, v18
	s_nop 0
	v_add_f32_e32 v18, 1.0, v18
	v_rcp_f32_e32 v18, v18
	s_nop 0
	v_mul_f32_e32 v16, v18, v16
	v_mul_f32_e32 v13, v13, v16
	v_cvt_pk_bf16_f32 v12, v12, v13
	v_lshlrev_b32_e32 v13, 16, v17
	v_mul_f32_e32 v16, 0xbfb8aa3b, v13
	v_exp_f32_e32 v16, v16
	s_nop 0
	v_add_f32_e32 v16, 1.0, v16
	v_rcp_f32_e32 v16, v16
	s_nop 0
	v_mul_f32_e32 v13, v16, v13
	v_mul_f32_e32 v13, v14, v13
	v_and_b32_e32 v14, 0xffff0000, v17
	v_mul_f32_e32 v16, 0xbfb8aa3b, v14
	v_exp_f32_e32 v16, v16
	s_nop 0
	v_add_f32_e32 v16, 1.0, v16
	v_rcp_f32_e32 v16, v16
	s_nop 0
	v_mul_f32_e32 v14, v16, v14
	v_mul_f32_e32 v14, v15, v14
	v_cvt_pk_bf16_f32 v13, v13, v14
	global_store_dwordx2 v[28:29], v[12:13], off offset:128
	s_nop 1
	v_mov_b32_e32 v12, v182
	v_mov_b32_e32 v13, v183
	v_lshlrev_b32_e32 v14, 16, v12
	v_mul_f32_e32 v15, 0xbfb8aa3b, v14
	v_exp_f32_e32 v15, v15
	v_and_b32_e32 v12, 0xffff0000, v12
	v_add_f32_e32 v15, 1.0, v15
	v_rcp_f32_e32 v15, v15
	s_nop 0
	v_mul_f32_e32 v14, v15, v14
	v_mul_f32_e32 v8, v8, v14
	v_mul_f32_e32 v14, 0xbfb8aa3b, v12
	v_exp_f32_e32 v14, v14
	s_nop 0
	v_add_f32_e32 v14, 1.0, v14
	v_rcp_f32_e32 v14, v14
	s_nop 0
	v_mul_f32_e32 v12, v14, v12
	v_mul_f32_e32 v9, v9, v12
	v_cvt_pk_bf16_f32 v8, v8, v9
	v_lshlrev_b32_e32 v9, 16, v13
	v_mul_f32_e32 v12, 0xbfb8aa3b, v9
	v_exp_f32_e32 v12, v12
	s_nop 0
	v_add_f32_e32 v12, 1.0, v12
	v_rcp_f32_e32 v12, v12
	s_nop 0
	v_mul_f32_e32 v9, v12, v9
	v_mul_f32_e32 v9, v10, v9
	v_and_b32_e32 v10, 0xffff0000, v13
	v_mul_f32_e32 v12, 0xbfb8aa3b, v10
	v_exp_f32_e32 v12, v12
	s_nop 0
	v_add_f32_e32 v12, 1.0, v12
	v_rcp_f32_e32 v12, v12
	s_nop 0
	v_mul_f32_e32 v10, v12, v10
	v_mul_f32_e32 v10, v11, v10
	v_cvt_pk_bf16_f32 v9, v9, v10
	global_store_dwordx2 v[28:29], v[8:9], off offset:160
	s_nop 1
	v_mov_b32_e32 v8, v184
	v_mov_b32_e32 v9, v185
	v_lshlrev_b32_e32 v10, 16, v8
	v_mul_f32_e32 v11, 0xbfb8aa3b, v10
	v_exp_f32_e32 v11, v11
	v_and_b32_e32 v8, 0xffff0000, v8
	v_add_f32_e32 v11, 1.0, v11
	v_rcp_f32_e32 v11, v11
	s_nop 0
	v_mul_f32_e32 v10, v11, v10
	v_mul_f32_e32 v4, v4, v10
	v_mul_f32_e32 v10, 0xbfb8aa3b, v8
	v_exp_f32_e32 v10, v10
	s_nop 0
	v_add_f32_e32 v10, 1.0, v10
	v_rcp_f32_e32 v10, v10
	s_nop 0
	v_mul_f32_e32 v8, v10, v8
	v_mul_f32_e32 v5, v5, v8
	v_cvt_pk_bf16_f32 v4, v4, v5
	v_lshlrev_b32_e32 v5, 16, v9
	v_mul_f32_e32 v8, 0xbfb8aa3b, v5
	v_exp_f32_e32 v8, v8
	s_nop 0
	v_add_f32_e32 v8, 1.0, v8
	v_rcp_f32_e32 v8, v8
	s_nop 0
	v_mul_f32_e32 v5, v8, v5
	v_mul_f32_e32 v5, v6, v5
	v_and_b32_e32 v6, 0xffff0000, v9
	v_mul_f32_e32 v8, 0xbfb8aa3b, v6
	v_exp_f32_e32 v8, v8
	s_nop 0
	v_add_f32_e32 v8, 1.0, v8
	v_rcp_f32_e32 v8, v8
	s_nop 0
	v_mul_f32_e32 v6, v8, v6
	v_mul_f32_e32 v6, v7, v6
	v_cvt_pk_bf16_f32 v5, v5, v6
	global_store_dwordx2 v[28:29], v[4:5], off offset:192
	s_nop 1
	v_mov_b32_e32 v4, v186
	v_mov_b32_e32 v5, v187
	v_lshlrev_b32_e32 v6, 16, v4
	v_mul_f32_e32 v7, 0xbfb8aa3b, v6
	v_exp_f32_e32 v7, v7
	v_and_b32_e32 v4, 0xffff0000, v4
	v_add_f32_e32 v7, 1.0, v7
	v_rcp_f32_e32 v7, v7
	s_nop 0
	v_mul_f32_e32 v6, v7, v6
	v_mul_f32_e32 v0, v0, v6
	v_mul_f32_e32 v6, 0xbfb8aa3b, v4
	v_exp_f32_e32 v6, v6
	s_nop 0
	v_add_f32_e32 v6, 1.0, v6
	v_rcp_f32_e32 v6, v6
	s_nop 0
	v_mul_f32_e32 v4, v6, v4
	v_mul_f32_e32 v1, v1, v4
	v_cvt_pk_bf16_f32 v0, v0, v1
	v_lshlrev_b32_e32 v1, 16, v5
	v_mul_f32_e32 v4, 0xbfb8aa3b, v1
	v_exp_f32_e32 v4, v4
	s_nop 0
	v_add_f32_e32 v4, 1.0, v4
	v_rcp_f32_e32 v4, v4
	s_nop 0
	v_mul_f32_e32 v1, v4, v1
	v_mul_f32_e32 v1, v2, v1
	v_and_b32_e32 v2, 0xffff0000, v5
	v_mul_f32_e32 v4, 0xbfb8aa3b, v2
	v_exp_f32_e32 v4, v4
	s_nop 0
	v_add_f32_e32 v4, 1.0, v4
	v_rcp_f32_e32 v4, v4
	s_nop 0
	v_mul_f32_e32 v2, v4, v2
	v_mul_f32_e32 v2, v3, v2
	v_cvt_pk_bf16_f32 v1, v1, v2
	global_store_dwordx2 v[28:29], v[0:1], off offset:224
	s_cbranch_vccnz .LBB0_268
	s_branch .LBB0_117

; DI void rms_row(const float* xrow, const float* g, u16* orow, int lane) {
;   const f32x4* xr = (const f32x4*)xrow + lane; const f32x4* gr = (const f32x4*)g + lane;
;   f32x4 v[8]; float s = 0.f;
; #pragma unroll
;   for (int j = 0; j < 8; ++j) { v[j] = xr[64 * j]; s += (v[j].x * v[j].x + v[j].y * v[j].y) + (v[j].z * v[j].z + v[j].w * v[j].w); }
;   const float rstd = rsqrtf(wave_sum(s, lane) * (1.f / DM) + EPS);
;   u32x2* o8 = (u32x2*)orow + lane;
; DI void phase_prologue(CP& p, LAS unsigned char* lds) {
;     ...
;       else if (r < TVAL) rms_row(p.in[1] + (size_t)(r - TP) * DM, p.in[8], h + (size_t)r * DM, lane);
.LBB0_375:
	s_andn2_saveexec_b64 s[58:59], s[58:59]
	s_cbranch_execz .LBB0_377
	v_add_u32_e32 v0, 0xffff2800, v33
	v_mov_b32_e32 v1, v147
	v_lshlrev_b64 v[0:1], 13, v[0:1]
	v_lshl_add_u64 v[0:1], v[24:25], 0, v[0:1]
	global_load_dwordx4 v[4:7], v[0:1], off
	global_load_dwordx4 v[8:11], v[0:1], off offset:1024
	global_load_dwordx4 v[12:15], v[0:1], off offset:2048
	global_load_dwordx4 v[16:19], v[0:1], off offset:3072
	v_add_co_u32_e32 v100, vcc, s78, v0
	s_waitcnt vmcnt(3)
	v_mov_b32_e32 v110, v5
	v_addc_co_u32_e32 v101, vcc, 0, v1, vcc
	global_load_dwordx4 v[92:95], v[100:101], off
	global_load_dwordx4 v[96:99], v[100:101], off offset:1024
	global_load_dwordx4 v[0:3], v[100:101], off offset:3072
	s_nop 0
	global_load_dwordx4 v[100:103], v[100:101], off offset:2048
	s_nop 0
	global_load_dwordx4 v[104:107], v[26:27], off
	global_load_dwordx4 v[148:151], v[26:27], off offset:1024
	global_load_dwordx4 v[152:155], v[26:27], off offset:2048
	global_load_dwordx4 v[156:159], v[26:27], off offset:3072
	global_load_dwordx4 v[160:163], v[30:31], off
	global_load_dwordx4 v[164:167], v[38:39], off
	global_load_dwordx4 v[168:171], v[40:41], off
	global_load_dwordx4 v[172:175], v[42:43], off
	s_waitcnt vmcnt(14)
	v_mov_b32_e32 v111, v9
	v_mov_b32_e32 v114, v7
	v_mov_b32_e32 v115, v11
	v_mov_b32_e32 v108, v4
	v_mov_b32_e32 v109, v8
	v_mov_b32_e32 v112, v6
	v_mov_b32_e32 v113, v10
	s_waitcnt vmcnt(13)
	v_pk_mul_f32 v[116:117], v[14:15], v[14:15]
	v_pk_mul_f32 v[118:119], v[12:13], v[12:13]
	v_pk_mul_f32 v[110:111], v[110:111], v[110:111]
	v_pk_mul_f32 v[114:115], v[114:115], v[114:115]
	v_pk_mov_b32 v[124:125], v[118:119], v[116:117] op_sel:[1,0]
	v_mov_b32_e32 v119, v117
	v_pk_fma_f32 v[108:109], v[108:109], v[108:109], v[110:111]
	v_pk_fma_f32 v[110:111], v[112:113], v[112:113], v[114:115]
	s_waitcnt vmcnt(12)
	v_mul_f32_e32 v120, v17, v17
	v_mul_f32_e32 v122, v19, v19
	v_pk_add_f32 v[112:113], v[124:125], v[118:119]
	v_pk_add_f32 v[108:109], v[108:109], v[110:111]
	v_pk_fma_f32 v[116:117], v[16:17], v[16:17], v[120:121] op_sel_hi:[1,1,0]
	v_pk_fma_f32 v[120:121], v[18:19], v[18:19], v[122:123] op_sel_hi:[1,1,0]
	v_pk_add_f32 v[110:111], v[112:113], v[112:113] op_sel:[0,1] op_sel_hi:[1,0]
	v_pk_add_f32 v[108:109], v[108:109], v[108:109] op_sel:[0,1] op_sel_hi:[1,0]
	s_waitcnt vmcnt(11)
	v_mul_f32_e32 v37, v92, v92
	v_mul_f32_e32 v129, v93, v93
	v_mul_f32_e32 v131, v94, v94
	v_mul_f32_e32 v132, v95, v95
	s_waitcnt vmcnt(10)
	v_pk_mul_f32 v[122:123], v[98:99], v[98:99]
	v_pk_mul_f32 v[126:127], v[96:97], v[96:97]
	v_mov_b32_e32 v117, v131
	v_mov_b32_e32 v121, v132
	v_mov_b32_e32 v111, v129
	v_mov_b32_e32 v109, v37
	v_pk_mov_b32 v[114:115], v[126:127], v[122:123] op_sel:[1,0]
	v_mov_b32_e32 v127, v123
	v_pk_add_f32 v[112:113], v[116:117], v[120:121]
	v_pk_add_f32 v[108:109], v[108:109], v[110:111]
	s_waitcnt vmcnt(8)
	v_mul_f32_e32 v128, v101, v101
	v_mul_f32_e32 v130, v103, v103
	v_pk_add_f32 v[114:115], v[114:115], v[126:127]
	v_pk_add_f32 v[108:109], v[108:109], v[112:113]
	v_mul_f32_e32 v133, v0, v0
	v_mul_f32_e32 v134, v1, v1
	v_mul_f32_e32 v135, v2, v2
	v_mul_f32_e32 v136, v3, v3
	v_pk_fma_f32 v[118:119], v[100:101], v[100:101], v[128:129] op_sel_hi:[1,1,0]
	v_pk_fma_f32 v[122:123], v[102:103], v[102:103], v[130:131] op_sel_hi:[1,1,0]
	v_pk_add_f32 v[114:115], v[114:115], v[114:115] op_sel:[0,1] op_sel_hi:[1,0]
	v_pk_add_f32 v[108:109], v[108:109], v[108:109] op_sel:[0,1] op_sel_hi:[1,0]
	v_mov_b32_e32 v119, v135
	v_mov_b32_e32 v123, v136
	v_mov_b32_e32 v115, v134
	v_mov_b32_e32 v109, v133
	v_pk_add_f32 v[116:117], v[118:119], v[122:123]
	v_pk_add_f32 v[108:109], v[108:109], v[114:115]
	s_nop 0
	v_pk_add_f32 v[108:109], v[108:109], v[116:117]
	s_nop 0
	v_add_f32_e32 v37, v108, v109
	ds_swizzle_b32 v108, v37 offset:swizzle(SWAP,1)
	s_waitcnt lgkmcnt(0)
	v_add_f32_e32 v37, v37, v108
	ds_swizzle_b32 v108, v37 offset:swizzle(SWAP,2)
	s_waitcnt lgkmcnt(0)
	v_add_f32_e32 v37, v37, v108
	ds_swizzle_b32 v108, v37 offset:swizzle(SWAP,4)
	s_waitcnt lgkmcnt(0)
	v_add_f32_e32 v37, v37, v108
	ds_swizzle_b32 v108, v37 offset:swizzle(SWAP,8)
	s_waitcnt lgkmcnt(0)
; DI unsigned pk2(float lo, float hi) { unsigned r; asm("v_cvt_pk_bf16_f32 %0, %1, %2" : "=v"(r) : "v"(lo), "v"(hi)); return r; }
; DI void rms_row(const float* xrow, const float* g, u16* orow, int lane) {
;     ...
;   const float rstd = rsqrtf(wave_sum(s, lane) * (1.f / DM) + EPS);
;   u32x2* o8 = (u32x2*)orow + lane;
; #pragma unroll
;   for (int j = 0; j < 8; ++j) { const f32x4 gg = gr[64 * j]; u32x2 o; o.x = pk2(v[j].x * rstd * gg.x, v[j].y * rstd * gg.y); o.y = pk2(v[j].z * rstd * gg.z, v[j].w * rstd * gg.w); o8[64 * j] = o; }
	v_add_f32_e32 v37, v37, v108
	ds_swizzle_b32 v108, v37 offset:swizzle(SWAP,16)
	s_waitcnt lgkmcnt(0)
	v_add_f32_e32 v37, v37, v108
	ds_bpermute_b32 v108, v35, v37
	s_waitcnt lgkmcnt(0)
	v_add_f32_e32 v37, v37, v108
	v_fmamk_f32 v37, v37, 0x3a000000, v234
	v_mul_f32_e32 v108, 0x4b800000, v37
	v_cmp_gt_f32_e32 vcc, s81, v37
	s_nop 1
	v_cndmask_b32_e32 v37, v37, v108, vcc
	v_rsq_f32_e32 v37, v37
	v_lshlrev_b64 v[108:109], 12, v[146:147]
	v_lshl_add_u64 v[108:109], v[28:29], 0, v[108:109]
	v_mul_f32_e32 v110, 0x45800000, v37
	v_cndmask_b32_e32 v37, v37, v110, vcc
	v_mul_f32_e32 v4, v4, v37
	v_mul_f32_e32 v5, v5, v37
	v_mul_f32_e32 v6, v6, v37
	v_mul_f32_e32 v7, v7, v37
	s_waitcnt vmcnt(7)
	v_mul_f32_e32 v4, v104, v4
	v_mul_f32_e32 v5, v105, v5
	v_mul_f32_e32 v6, v106, v6
	v_mul_f32_e32 v7, v107, v7
	v_cvt_pk_bf16_f32 v4, v4, v5
	v_cvt_pk_bf16_f32 v5, v6, v7
	global_store_dwordx2 v[108:109], v[4:5], off
	v_mul_f32_e32 v8, v8, v37
	v_mul_f32_e32 v9, v9, v37
	v_mul_f32_e32 v10, v10, v37
	v_mul_f32_e32 v11, v11, v37
	v_mul_f32_e32 v0, v0, v37
	v_mul_f32_e32 v1, v1, v37
	v_mul_f32_e32 v2, v2, v37
	v_mul_f32_e32 v3, v3, v37
	s_waitcnt vmcnt(7)
	v_mov_b32_e32 v4, v148
	v_mov_b32_e32 v5, v149
	v_mov_b32_e32 v6, v150
	v_mov_b32_e32 v7, v151
	v_mul_f32_e32 v4, v4, v8
	v_mul_f32_e32 v5, v5, v9
	v_mul_f32_e32 v6, v6, v10
	v_mul_f32_e32 v7, v7, v11
	v_cvt_pk_bf16_f32 v4, v4, v5
	v_cvt_pk_bf16_f32 v5, v6, v7
	global_store_dwordx2 v[108:109], v[4:5], off offset:512
	v_mul_f32_e32 v8, v12, v37
	v_mul_f32_e32 v9, v13, v37
	v_mul_f32_e32 v10, v14, v37
	v_mul_f32_e32 v11, v15, v37
	s_waitcnt vmcnt(7)
	v_mov_b32_e32 v4, v152
	v_mov_b32_e32 v5, v153
	v_mov_b32_e32 v6, v154
	v_mov_b32_e32 v7, v155
	v_mul_f32_e32 v4, v4, v8
	v_mul_f32_e32 v5, v5, v9
	v_mul_f32_e32 v6, v6, v10
	v_mul_f32_e32 v7, v7, v11
	v_cvt_pk_bf16_f32 v4, v4, v5
	v_cvt_pk_bf16_f32 v5, v6, v7
	global_store_dwordx2 v[108:109], v[4:5], off offset:1024
	v_mul_f32_e32 v8, v16, v37
	v_mul_f32_e32 v9, v17, v37
	v_mul_f32_e32 v10, v18, v37
	v_mul_f32_e32 v11, v19, v37
	s_waitcnt vmcnt(7)
	v_mov_b32_e32 v4, v156
	v_mov_b32_e32 v5, v157
	v_mov_b32_e32 v6, v158
	v_mov_b32_e32 v7, v159
	v_mul_f32_e32 v4, v8, v4
	v_mul_f32_e32 v5, v9, v5
	v_mul_f32_e32 v6, v10, v6
	v_mul_f32_e32 v7, v11, v7
	v_cvt_pk_bf16_f32 v4, v4, v5
	v_cvt_pk_bf16_f32 v5, v6, v7
	global_store_dwordx2 v[108:109], v[4:5], off offset:1536
	v_mul_f32_e32 v8, v92, v37
	v_mul_f32_e32 v9, v93, v37
	v_mul_f32_e32 v10, v94, v37
	v_mul_f32_e32 v11, v95, v37
	s_waitcnt vmcnt(7)
	v_mov_b32_e32 v4, v160
	v_mov_b32_e32 v5, v161
	v_mov_b32_e32 v6, v162
	v_mov_b32_e32 v7, v163
	v_mul_f32_e32 v4, v8, v4
	v_mul_f32_e32 v5, v9, v5
	v_mul_f32_e32 v6, v10, v6
	v_mul_f32_e32 v7, v11, v7
	v_cvt_pk_bf16_f32 v4, v4, v5
	v_cvt_pk_bf16_f32 v5, v6, v7
	global_store_dwordx2 v[108:109], v[4:5], off offset:2048
	v_mul_f32_e32 v8, v96, v37
	v_mul_f32_e32 v9, v97, v37
	v_mul_f32_e32 v10, v98, v37
	v_mul_f32_e32 v11, v99, v37
	s_waitcnt vmcnt(7)
	v_mov_b32_e32 v4, v164
	v_mov_b32_e32 v5, v165
	v_mov_b32_e32 v6, v166
	v_mov_b32_e32 v7, v167
	v_mul_f32_e32 v4, v8, v4
	v_mul_f32_e32 v5, v9, v5
	v_mul_f32_e32 v6, v10, v6
	v_mul_f32_e32 v7, v11, v7
	v_cvt_pk_bf16_f32 v4, v4, v5
	v_cvt_pk_bf16_f32 v5, v6, v7
	global_store_dwordx2 v[108:109], v[4:5], off offset:2560
	v_mul_f32_e32 v8, v100, v37
	v_mul_f32_e32 v9, v101, v37
	v_mul_f32_e32 v10, v102, v37
	v_mul_f32_e32 v11, v103, v37
	s_waitcnt vmcnt(7)
	v_mov_b32_e32 v4, v168
	v_mov_b32_e32 v5, v169
	v_mov_b32_e32 v6, v170
	v_mov_b32_e32 v7, v171
	v_mul_f32_e32 v4, v8, v4
	v_mul_f32_e32 v5, v9, v5
	v_mul_f32_e32 v6, v10, v6
	v_mul_f32_e32 v7, v11, v7
	v_cvt_pk_bf16_f32 v4, v4, v5
	v_cvt_pk_bf16_f32 v5, v6, v7
	global_store_dwordx2 v[108:109], v[4:5], off offset:3072
	s_waitcnt vmcnt(7)
	v_mov_b32_e32 v4, v172
	v_mov_b32_e32 v5, v173
	v_mov_b32_e32 v6, v174
	v_mov_b32_e32 v7, v175
	v_mul_f32_e32 v0, v0, v4
	v_mul_f32_e32 v1, v1, v5
	v_mul_f32_e32 v2, v2, v6
	v_mul_f32_e32 v3, v3, v7
	v_cvt_pk_bf16_f32 v0, v0, v1
	v_cvt_pk_bf16_f32 v1, v2, v3
	global_store_dwordx2 v[108:109], v[0:1], off offset:3584

; DI void rms_row(const float* xrow, const float* g, u16* orow, int lane) {
;   const f32x4* xr = (const f32x4*)xrow + lane; const f32x4* gr = (const f32x4*)g + lane;
;   f32x4 v[8]; float s = 0.f;
; #pragma unroll
;   for (int j = 0; j < 8; ++j) { v[j] = xr[64 * j]; s += (v[j].x * v[j].x + v[j].y * v[j].y) + (v[j].z * v[j].z + v[j].w * v[j].w); }
;   const float rstd = rsqrtf(wave_sum(s, lane) * (1.f / DM) + EPS);
;   u32x2* o8 = (u32x2*)orow + lane;
; DI void phase_prologue(CP& p, LAS unsigned char* lds) {
;     ...
;       if (r < TP) rms_row(p.in[0] + (size_t)r * DM, p.in[8], h + (size_t)r * DM, lane);
.LBB0_378:
	s_andn2_saveexec_b64 s[26:27], s[26:27]
	s_cbranch_execz .LBB0_380
	v_lshlrev_b64 v[0:1], 13, v[146:147]
	v_lshl_add_u64 v[0:1], v[44:45], 0, v[0:1]
	global_load_dwordx4 v[4:7], v[0:1], off
	global_load_dwordx4 v[8:11], v[0:1], off offset:1024
	global_load_dwordx4 v[12:15], v[0:1], off offset:2048
	global_load_dwordx4 v[16:19], v[0:1], off offset:3072
	v_add_co_u32_e32 v100, vcc, s78, v0
	s_waitcnt vmcnt(3)
	v_mov_b32_e32 v110, v5
	v_addc_co_u32_e32 v101, vcc, 0, v1, vcc
	global_load_dwordx4 v[92:95], v[100:101], off
	global_load_dwordx4 v[96:99], v[100:101], off offset:1024
	global_load_dwordx4 v[0:3], v[100:101], off offset:3072
	s_nop 0
	global_load_dwordx4 v[100:103], v[100:101], off offset:2048
	s_nop 0
	global_load_dwordx4 v[104:107], v[26:27], off
	global_load_dwordx4 v[148:151], v[26:27], off offset:1024
	global_load_dwordx4 v[152:155], v[26:27], off offset:2048
	global_load_dwordx4 v[156:159], v[26:27], off offset:3072
	global_load_dwordx4 v[160:163], v[30:31], off
	global_load_dwordx4 v[164:167], v[38:39], off
	global_load_dwordx4 v[168:171], v[40:41], off
	global_load_dwordx4 v[172:175], v[42:43], off
	s_waitcnt vmcnt(14)
	v_mov_b32_e32 v111, v9
	v_mov_b32_e32 v114, v7
	v_mov_b32_e32 v115, v11
	v_mov_b32_e32 v108, v4
	v_mov_b32_e32 v109, v8
	v_mov_b32_e32 v112, v6
	v_mov_b32_e32 v113, v10
	s_waitcnt vmcnt(13)
	v_pk_mul_f32 v[116:117], v[14:15], v[14:15]
	v_pk_mul_f32 v[118:119], v[12:13], v[12:13]
	v_pk_mul_f32 v[110:111], v[110:111], v[110:111]
	v_pk_mul_f32 v[114:115], v[114:115], v[114:115]
	v_pk_mov_b32 v[124:125], v[118:119], v[116:117] op_sel:[1,0]
	v_mov_b32_e32 v119, v117
	v_pk_fma_f32 v[108:109], v[108:109], v[108:109], v[110:111]
	v_pk_fma_f32 v[110:111], v[112:113], v[112:113], v[114:115]
	s_waitcnt vmcnt(12)
	v_mul_f32_e32 v120, v17, v17
	v_mul_f32_e32 v122, v19, v19
	v_pk_add_f32 v[112:113], v[124:125], v[118:119]
	v_pk_add_f32 v[108:109], v[108:109], v[110:111]
	v_pk_fma_f32 v[116:117], v[16:17], v[16:17], v[120:121] op_sel_hi:[1,1,0]
	v_pk_fma_f32 v[120:121], v[18:19], v[18:19], v[122:123] op_sel_hi:[1,1,0]
	v_pk_add_f32 v[110:111], v[112:113], v[112:113] op_sel:[0,1] op_sel_hi:[1,0]
	v_pk_add_f32 v[108:109], v[108:109], v[108:109] op_sel:[0,1] op_sel_hi:[1,0]
	s_waitcnt vmcnt(11)
	v_mul_f32_e32 v37, v92, v92
	v_mul_f32_e32 v129, v93, v93
	v_mul_f32_e32 v131, v94, v94
	v_mul_f32_e32 v132, v95, v95
	s_waitcnt vmcnt(10)
	v_pk_mul_f32 v[122:123], v[98:99], v[98:99]
	v_pk_mul_f32 v[126:127], v[96:97], v[96:97]
	v_mov_b32_e32 v117, v131
	v_mov_b32_e32 v121, v132
	v_mov_b32_e32 v111, v129
	v_mov_b32_e32 v109, v37
	v_pk_mov_b32 v[114:115], v[126:127], v[122:123] op_sel:[1,0]
	v_mov_b32_e32 v127, v123
	v_pk_add_f32 v[112:113], v[116:117], v[120:121]
	v_pk_add_f32 v[108:109], v[108:109], v[110:111]
	s_waitcnt vmcnt(8)
	v_mul_f32_e32 v128, v101, v101
	v_mul_f32_e32 v130, v103, v103
	v_pk_add_f32 v[114:115], v[114:115], v[126:127]
	v_pk_add_f32 v[108:109], v[108:109], v[112:113]
	v_mul_f32_e32 v133, v0, v0
	v_mul_f32_e32 v134, v1, v1
	v_mul_f32_e32 v135, v2, v2
	v_mul_f32_e32 v136, v3, v3
	v_pk_fma_f32 v[118:119], v[100:101], v[100:101], v[128:129] op_sel_hi:[1,1,0]
	v_pk_fma_f32 v[122:123], v[102:103], v[102:103], v[130:131] op_sel_hi:[1,1,0]
	v_pk_add_f32 v[114:115], v[114:115], v[114:115] op_sel:[0,1] op_sel_hi:[1,0]
	v_pk_add_f32 v[108:109], v[108:109], v[108:109] op_sel:[0,1] op_sel_hi:[1,0]
	v_mov_b32_e32 v119, v135
	v_mov_b32_e32 v123, v136
	v_mov_b32_e32 v115, v134
	v_mov_b32_e32 v109, v133
	v_pk_add_f32 v[116:117], v[118:119], v[122:123]
	v_pk_add_f32 v[108:109], v[108:109], v[114:115]
	s_nop 0
	v_pk_add_f32 v[108:109], v[108:109], v[116:117]
	s_nop 0
	v_add_f32_e32 v37, v108, v109
	ds_swizzle_b32 v108, v37 offset:swizzle(SWAP,1)
	s_waitcnt lgkmcnt(0)
	v_add_f32_e32 v37, v37, v108
	ds_swizzle_b32 v108, v37 offset:swizzle(SWAP,2)
	s_waitcnt lgkmcnt(0)
	v_add_f32_e32 v37, v37, v108
	ds_swizzle_b32 v108, v37 offset:swizzle(SWAP,4)
	s_waitcnt lgkmcnt(0)
	v_add_f32_e32 v37, v37, v108
	ds_swizzle_b32 v108, v37 offset:swizzle(SWAP,8)
	s_waitcnt lgkmcnt(0)
; DI unsigned pk2(float lo, float hi) { unsigned r; asm("v_cvt_pk_bf16_f32 %0, %1, %2" : "=v"(r) : "v"(lo), "v"(hi)); return r; }
; DI void rms_row(const float* xrow, const float* g, u16* orow, int lane) {
;     ...
;   const float rstd = rsqrtf(wave_sum(s, lane) * (1.f / DM) + EPS);
;   u32x2* o8 = (u32x2*)orow + lane;
; #pragma unroll
;   for (int j = 0; j < 8; ++j) { const f32x4 gg = gr[64 * j]; u32x2 o; o.x = pk2(v[j].x * rstd * gg.x, v[j].y * rstd * gg.y); o.y = pk2(v[j].z * rstd * gg.z, v[j].w * rstd * gg.w); o8[64 * j] = o; }
	v_add_f32_e32 v37, v37, v108
	ds_swizzle_b32 v108, v37 offset:swizzle(SWAP,16)
	s_waitcnt lgkmcnt(0)
	v_add_f32_e32 v37, v37, v108
	ds_bpermute_b32 v108, v35, v37
	s_waitcnt lgkmcnt(0)
	v_add_f32_e32 v37, v37, v108
	v_fmamk_f32 v37, v37, 0x3a000000, v234
	v_mul_f32_e32 v108, 0x4b800000, v37
	v_cmp_gt_f32_e32 vcc, s81, v37
	s_nop 1
	v_cndmask_b32_e32 v37, v37, v108, vcc
	v_rsq_f32_e32 v37, v37
	v_lshlrev_b64 v[108:109], 12, v[146:147]
	v_lshl_add_u64 v[108:109], v[28:29], 0, v[108:109]
	v_mul_f32_e32 v110, 0x45800000, v37
	v_cndmask_b32_e32 v37, v37, v110, vcc
	v_mul_f32_e32 v4, v4, v37
	v_mul_f32_e32 v5, v5, v37
	v_mul_f32_e32 v6, v6, v37
	v_mul_f32_e32 v7, v7, v37
	s_waitcnt vmcnt(7)
	v_mul_f32_e32 v4, v104, v4
	v_mul_f32_e32 v5, v105, v5
	v_mul_f32_e32 v6, v106, v6
	v_mul_f32_e32 v7, v107, v7
	v_cvt_pk_bf16_f32 v4, v4, v5
	v_cvt_pk_bf16_f32 v5, v6, v7
	global_store_dwordx2 v[108:109], v[4:5], off
	v_mul_f32_e32 v8, v8, v37
	v_mul_f32_e32 v9, v9, v37
	v_mul_f32_e32 v10, v10, v37
	v_mul_f32_e32 v11, v11, v37
	v_mul_f32_e32 v0, v0, v37
	v_mul_f32_e32 v1, v1, v37
	v_mul_f32_e32 v2, v2, v37
	v_mul_f32_e32 v3, v3, v37
	s_waitcnt vmcnt(7)
	v_mov_b32_e32 v4, v148
	v_mov_b32_e32 v5, v149
	v_mov_b32_e32 v6, v150
	v_mov_b32_e32 v7, v151
	v_mul_f32_e32 v4, v4, v8
	v_mul_f32_e32 v5, v5, v9
	v_mul_f32_e32 v6, v6, v10
	v_mul_f32_e32 v7, v7, v11
	v_cvt_pk_bf16_f32 v4, v4, v5
	v_cvt_pk_bf16_f32 v5, v6, v7
	global_store_dwordx2 v[108:109], v[4:5], off offset:512
	v_mul_f32_e32 v8, v12, v37
	v_mul_f32_e32 v9, v13, v37
	v_mul_f32_e32 v10, v14, v37
	v_mul_f32_e32 v11, v15, v37
	s_waitcnt vmcnt(7)
	v_mov_b32_e32 v4, v152
	v_mov_b32_e32 v5, v153
	v_mov_b32_e32 v6, v154
	v_mov_b32_e32 v7, v155
	v_mul_f32_e32 v4, v4, v8
	v_mul_f32_e32 v5, v5, v9
	v_mul_f32_e32 v6, v6, v10
	v_mul_f32_e32 v7, v7, v11
	v_cvt_pk_bf16_f32 v4, v4, v5
	v_cvt_pk_bf16_f32 v5, v6, v7
	global_store_dwordx2 v[108:109], v[4:5], off offset:1024
	v_mul_f32_e32 v8, v16, v37
	v_mul_f32_e32 v9, v17, v37
	v_mul_f32_e32 v10, v18, v37
	v_mul_f32_e32 v11, v19, v37
	s_waitcnt vmcnt(7)
	v_mov_b32_e32 v4, v156
	v_mov_b32_e32 v5, v157
	v_mov_b32_e32 v6, v158
	v_mov_b32_e32 v7, v159
	v_mul_f32_e32 v4, v8, v4
	v_mul_f32_e32 v5, v9, v5
	v_mul_f32_e32 v6, v10, v6
	v_mul_f32_e32 v7, v11, v7
	v_cvt_pk_bf16_f32 v4, v4, v5
	v_cvt_pk_bf16_f32 v5, v6, v7
	global_store_dwordx2 v[108:109], v[4:5], off offset:1536
	v_mul_f32_e32 v8, v92, v37
	v_mul_f32_e32 v9, v93, v37
	v_mul_f32_e32 v10, v94, v37
	v_mul_f32_e32 v11, v95, v37
	s_waitcnt vmcnt(7)
	v_mov_b32_e32 v4, v160
	v_mov_b32_e32 v5, v161
	v_mov_b32_e32 v6, v162
	v_mov_b32_e32 v7, v163
	v_mul_f32_e32 v4, v8, v4
	v_mul_f32_e32 v5, v9, v5
	v_mul_f32_e32 v6, v10, v6
	v_mul_f32_e32 v7, v11, v7
	v_cvt_pk_bf16_f32 v4, v4, v5
	v_cvt_pk_bf16_f32 v5, v6, v7
	global_store_dwordx2 v[108:109], v[4:5], off offset:2048
	v_mul_f32_e32 v8, v96, v37
	v_mul_f32_e32 v9, v97, v37
	v_mul_f32_e32 v10, v98, v37
	v_mul_f32_e32 v11, v99, v37
	s_waitcnt vmcnt(7)
	v_mov_b32_e32 v4, v164
	v_mov_b32_e32 v5, v165
	v_mov_b32_e32 v6, v166
	v_mov_b32_e32 v7, v167
	v_mul_f32_e32 v4, v8, v4
	v_mul_f32_e32 v5, v9, v5
	v_mul_f32_e32 v6, v10, v6
	v_mul_f32_e32 v7, v11, v7
	v_cvt_pk_bf16_f32 v4, v4, v5
	v_cvt_pk_bf16_f32 v5, v6, v7
	global_store_dwordx2 v[108:109], v[4:5], off offset:2560
	v_mul_f32_e32 v8, v100, v37
	v_mul_f32_e32 v9, v101, v37
	v_mul_f32_e32 v10, v102, v37
	v_mul_f32_e32 v11, v103, v37
	s_waitcnt vmcnt(7)
	v_mov_b32_e32 v4, v168
	v_mov_b32_e32 v5, v169
	v_mov_b32_e32 v6, v170
	v_mov_b32_e32 v7, v171
	v_mul_f32_e32 v4, v8, v4
	v_mul_f32_e32 v5, v9, v5
	v_mul_f32_e32 v6, v10, v6
	v_mul_f32_e32 v7, v11, v7
	v_cvt_pk_bf16_f32 v4, v4, v5
	v_cvt_pk_bf16_f32 v5, v6, v7
	global_store_dwordx2 v[108:109], v[4:5], off offset:3072
	s_waitcnt vmcnt(7)
	v_mov_b32_e32 v4, v172
	v_mov_b32_e32 v5, v173
	v_mov_b32_e32 v6, v174
	v_mov_b32_e32 v7, v175
	v_mul_f32_e32 v0, v0, v4
	v_mul_f32_e32 v1, v1, v5
	v_mul_f32_e32 v2, v2, v6
	v_mul_f32_e32 v3, v3, v7
	v_cvt_pk_bf16_f32 v0, v0, v1
	v_cvt_pk_bf16_f32 v1, v2, v3
	global_store_dwordx2 v[108:109], v[0:1], off offset:3584
